# cv46 + GEMM K-loops: scalar bookkeeping at the head of load segments 2-4 (base+step temporaries, LDS offsets, first M0 write) and the loop-bottom pointer/counter increments moved into the preceding MM
# baseline (speedup 1.0000x reference)
.LBB0_306:
	s_add_u32 s38, s36, 0xfff80080
	s_addc_u32 s39, s37, -1
	s_add_i32 s45, 0, 0x10000
	s_cmp_eq_u32 s27, 28
	s_cselect_b32 s43, s9, s39
	s_cselect_b32 s42, s14, s38
	v_add_u32_e32 v34, s45, v170
	s_cselect_b32 s39, s16, s26
	s_cselect_b32 s38, s17, s25
	s_add_i32 s47, 0, 0x14000
	ds_read_b128 v[160:163], v34
	ds_read_b128 v[164:167], v34 offset:1024
	ds_read_b128 v[174:177], v34 offset:2048
	ds_read_b128 v[184:187], v34 offset:3072
	v_add_u32_e32 v34, s47, v170
	ds_read_b128 v[188:191], v34
	ds_read_b128 v[192:195], v34 offset:1024
	ds_read_b128 v[196:199], v34 offset:2048
	ds_read_b128 v[200:203], v34 offset:3072
	s_add_i32 m0, s35, 0xc000
	ds_read_b128 v[214:217], v173
	ds_read_b128 v[218:221], v173 offset:1024
	ds_read_b128 v[222:225], v173 offset:2048
	ds_read_b128 v[226:229], v173 offset:3072
	ds_read_b128 v[230:233], v173 offset:4096
	ds_read_b128 v[234:237], v173 offset:5120
	ds_read_b128 v[238:241], v173 offset:6144
	ds_read_b128 v[242:245], v173 offset:7168
	global_load_lds_dwordx4 v152, s[36:37]
	s_add_i32 m0, s35, 0xe000
	s_nop 0
	global_load_lds_dwordx4 v156, s[36:37]
	s_waitcnt vmcnt(8)
	s_waitcnt lgkmcnt(0)
	s_barrier
	s_setprio 1
	s_waitcnt lgkmcnt(0)
	v_mfma_f32_16x16x32_bf16 v[132:135], v[160:163], v[214:217], v[132:135]
	v_mfma_f32_16x16x32_bf16 v[128:131], v[174:177], v[214:217], v[128:131]
	v_mfma_f32_16x16x32_bf16 v[116:119], v[160:163], v[222:225], v[116:119]
	s_add_u32 s98, s38, s22
	v_mfma_f32_16x16x32_bf16 v[112:115], v[174:177], v[222:225], v[112:115]
	s_addc_u32 s99, s39, s23
	v_mfma_f32_16x16x32_bf16 v[100:103], v[160:163], v[230:233], v[100:103]
	s_add_u32 s100, s42, s22
	v_mfma_f32_16x16x32_bf16 v[96:99], v[174:177], v[230:233], v[96:99]
	s_addc_u32 s101, s43, s23
	v_mfma_f32_16x16x32_bf16 v[84:87], v[160:163], v[238:241], v[84:87]
	s_add_i32 s45, s45, s53
	v_mfma_f32_16x16x32_bf16 v[80:83], v[174:177], v[238:241], v[80:83]
	s_mov_b32 m0, s45
	v_mfma_f32_16x16x32_bf16 v[132:135], v[164:167], v[218:221], v[132:135]
	v_mfma_f32_16x16x32_bf16 v[128:131], v[184:187], v[218:221], v[128:131]
	v_mfma_f32_16x16x32_bf16 v[116:119], v[164:167], v[226:229], v[116:119]
	v_mfma_f32_16x16x32_bf16 v[112:115], v[184:187], v[226:229], v[112:115]
	v_mfma_f32_16x16x32_bf16 v[100:103], v[164:167], v[234:237], v[100:103]
	v_mfma_f32_16x16x32_bf16 v[96:99], v[184:187], v[234:237], v[96:99]
	v_mfma_f32_16x16x32_bf16 v[84:87], v[164:167], v[242:245], v[84:87]
	v_mfma_f32_16x16x32_bf16 v[80:83], v[184:187], v[242:245], v[80:83]
	s_setprio 0
	s_setprio 1
	v_mfma_f32_16x16x32_bf16 v[124:127], v[188:191], v[214:217], v[124:127]
	v_mfma_f32_16x16x32_bf16 v[120:123], v[196:199], v[214:217], v[120:123]
	v_mfma_f32_16x16x32_bf16 v[108:111], v[188:191], v[222:225], v[108:111]
	v_mfma_f32_16x16x32_bf16 v[104:107], v[196:199], v[222:225], v[104:107]
	v_mfma_f32_16x16x32_bf16 v[92:95], v[188:191], v[230:233], v[92:95]
	v_mfma_f32_16x16x32_bf16 v[88:91], v[196:199], v[230:233], v[88:91]
	v_mfma_f32_16x16x32_bf16 v[76:79], v[188:191], v[238:241], v[76:79]
	v_mfma_f32_16x16x32_bf16 v[72:75], v[196:199], v[238:241], v[72:75]
	v_mfma_f32_16x16x32_bf16 v[124:127], v[192:195], v[218:221], v[124:127]
	v_mfma_f32_16x16x32_bf16 v[120:123], v[200:203], v[218:221], v[120:123]
	v_mfma_f32_16x16x32_bf16 v[108:111], v[192:195], v[226:229], v[108:111]
	v_mfma_f32_16x16x32_bf16 v[104:107], v[200:203], v[226:229], v[104:107]
	v_mfma_f32_16x16x32_bf16 v[92:95], v[192:195], v[234:237], v[92:95]
	v_mfma_f32_16x16x32_bf16 v[88:91], v[200:203], v[234:237], v[88:91]
	v_mfma_f32_16x16x32_bf16 v[76:79], v[192:195], v[242:245], v[76:79]
	v_mfma_f32_16x16x32_bf16 v[72:75], v[200:203], v[242:245], v[72:75]
	s_setprio 0
	s_barrier
	ds_read_b128 v[214:217], v173 offset:16384
	ds_read_b128 v[218:221], v173 offset:17408
	ds_read_b128 v[222:225], v173 offset:18432
	ds_read_b128 v[226:229], v173 offset:19456
	ds_read_b128 v[230:233], v173 offset:20480
	ds_read_b128 v[234:237], v173 offset:21504
	ds_read_b128 v[238:241], v173 offset:22528
	ds_read_b128 v[242:245], v173 offset:23552
	global_load_lds_dwordx4 v136, s[38:39]
	s_add_i32 m0, s45, 0x2000
	s_add_u32 s70, s38, 0x80000
	s_addc_u32 s71, s39, 0
	s_add_i32 s45, s47, s53
	global_load_lds_dwordx4 v140, s[38:39]
	s_mov_b32 m0, s45
	s_nop 0
	global_load_lds_dwordx4 v136, s[70:71]
	s_add_i32 m0, s45, 0x2000
	s_nop 0
	global_load_lds_dwordx4 v140, s[70:71]
	s_mov_b32 m0, s35
	s_nop 0
	global_load_lds_dwordx4 v14, s[42:43]
	s_mov_b32 m0, s54
	s_nop 0
	global_load_lds_dwordx4 v138, s[42:43]
	s_waitcnt vmcnt(8)
	s_waitcnt lgkmcnt(0)
	s_barrier
	s_setprio 1
	s_waitcnt lgkmcnt(0)
	v_mfma_f32_16x16x32_bf16 v[68:71], v[160:163], v[214:217], v[68:71]
	v_mfma_f32_16x16x32_bf16 v[64:67], v[174:177], v[214:217], v[64:67]
	v_mfma_f32_16x16x32_bf16 v[52:55], v[160:163], v[222:225], v[52:55]
	s_add_i32 s45, 0, 0x18000
	v_mfma_f32_16x16x32_bf16 v[48:51], v[174:177], v[222:225], v[48:51]
	v_mfma_f32_16x16x32_bf16 v[36:39], v[160:163], v[230:233], v[36:39]
	v_mfma_f32_16x16x32_bf16 v[30:33], v[174:177], v[230:233], v[30:33]
	v_mfma_f32_16x16x32_bf16 v[18:21], v[160:163], v[238:241], v[18:21]
	v_mfma_f32_16x16x32_bf16 v[10:13], v[174:177], v[238:241], v[10:13]
	v_mfma_f32_16x16x32_bf16 v[68:71], v[164:167], v[218:221], v[68:71]
	v_mfma_f32_16x16x32_bf16 v[64:67], v[184:187], v[218:221], v[64:67]
	v_mfma_f32_16x16x32_bf16 v[52:55], v[164:167], v[226:229], v[52:55]
	v_mfma_f32_16x16x32_bf16 v[48:51], v[184:187], v[226:229], v[48:51]
	v_mfma_f32_16x16x32_bf16 v[36:39], v[164:167], v[234:237], v[36:39]
	v_mfma_f32_16x16x32_bf16 v[30:33], v[184:187], v[234:237], v[30:33]
	v_mfma_f32_16x16x32_bf16 v[18:21], v[164:167], v[242:245], v[18:21]
	v_mfma_f32_16x16x32_bf16 v[10:13], v[184:187], v[242:245], v[10:13]
	s_setprio 0
	s_setprio 1
	v_mfma_f32_16x16x32_bf16 v[60:63], v[188:191], v[214:217], v[60:63]
	v_mfma_f32_16x16x32_bf16 v[56:59], v[196:199], v[214:217], v[56:59]
	v_mfma_f32_16x16x32_bf16 v[44:47], v[188:191], v[222:225], v[44:47]
	v_mfma_f32_16x16x32_bf16 v[40:43], v[196:199], v[222:225], v[40:43]
	v_mfma_f32_16x16x32_bf16 v[26:29], v[188:191], v[230:233], v[26:29]
	v_mfma_f32_16x16x32_bf16 v[22:25], v[196:199], v[230:233], v[22:25]
	v_mfma_f32_16x16x32_bf16 v[6:9], v[188:191], v[238:241], v[6:9]
	v_mfma_f32_16x16x32_bf16 v[2:5], v[196:199], v[238:241], v[2:5]
	v_mfma_f32_16x16x32_bf16 v[60:63], v[192:195], v[218:221], v[60:63]
	v_mfma_f32_16x16x32_bf16 v[56:59], v[200:203], v[218:221], v[56:59]
	v_mfma_f32_16x16x32_bf16 v[44:47], v[192:195], v[226:229], v[44:47]
	v_mfma_f32_16x16x32_bf16 v[40:43], v[200:203], v[226:229], v[40:43]
	v_mfma_f32_16x16x32_bf16 v[26:29], v[192:195], v[234:237], v[26:29]
	v_mfma_f32_16x16x32_bf16 v[22:25], v[200:203], v[234:237], v[22:25]
	v_mfma_f32_16x16x32_bf16 v[6:9], v[192:195], v[242:245], v[6:9]
	v_mfma_f32_16x16x32_bf16 v[2:5], v[200:203], v[242:245], v[2:5]
	s_setprio 0
	s_barrier
	v_add_u32_e32 v34, s45, v170
	s_add_i32 s47, 0, 0x1c000
	ds_read_b128 v[160:163], v34
	ds_read_b128 v[164:167], v34 offset:1024
	ds_read_b128 v[174:177], v34 offset:2048
	ds_read_b128 v[184:187], v34 offset:3072
	v_add_u32_e32 v34, s47, v170
	ds_read_b128 v[188:191], v34
	ds_read_b128 v[192:195], v34 offset:1024
	ds_read_b128 v[196:199], v34 offset:2048
	ds_read_b128 v[200:203], v34 offset:3072
	s_add_u32 s42, s42, 0x80000
	s_addc_u32 s43, s43, 0
	s_mov_b32 m0, s55
	ds_read_b128 v[214:217], v173 offset:32768
	ds_read_b128 v[218:221], v173 offset:33792
	ds_read_b128 v[222:225], v173 offset:34816
	ds_read_b128 v[226:229], v173 offset:35840
	ds_read_b128 v[230:233], v173 offset:36864
	ds_read_b128 v[234:237], v173 offset:37888
	ds_read_b128 v[238:241], v173 offset:38912
	ds_read_b128 v[242:245], v173 offset:39936
	global_load_lds_dwordx4 v14, s[42:43]
	s_mov_b32 m0, s60
	s_nop 0
	global_load_lds_dwordx4 v138, s[42:43]
	s_waitcnt vmcnt(8)
	s_waitcnt lgkmcnt(0)
	s_barrier
	s_setprio 1
	s_waitcnt lgkmcnt(0)
	v_mfma_f32_16x16x32_bf16 v[132:135], v[160:163], v[214:217], v[132:135]
	v_mfma_f32_16x16x32_bf16 v[128:131], v[174:177], v[214:217], v[128:131]
	v_mfma_f32_16x16x32_bf16 v[116:119], v[160:163], v[222:225], v[116:119]
	s_add_i32 s42, s45, s53
	v_mfma_f32_16x16x32_bf16 v[112:115], v[174:177], v[222:225], v[112:115]
	s_mov_b32 m0, s42
	v_mfma_f32_16x16x32_bf16 v[100:103], v[160:163], v[230:233], v[100:103]
	v_mfma_f32_16x16x32_bf16 v[96:99], v[174:177], v[230:233], v[96:99]
	v_mfma_f32_16x16x32_bf16 v[84:87], v[160:163], v[238:241], v[84:87]
	v_mfma_f32_16x16x32_bf16 v[80:83], v[174:177], v[238:241], v[80:83]
	v_mfma_f32_16x16x32_bf16 v[132:135], v[164:167], v[218:221], v[132:135]
	v_mfma_f32_16x16x32_bf16 v[128:131], v[184:187], v[218:221], v[128:131]
	v_mfma_f32_16x16x32_bf16 v[116:119], v[164:167], v[226:229], v[116:119]
	v_mfma_f32_16x16x32_bf16 v[112:115], v[184:187], v[226:229], v[112:115]
	v_mfma_f32_16x16x32_bf16 v[100:103], v[164:167], v[234:237], v[100:103]
	v_mfma_f32_16x16x32_bf16 v[96:99], v[184:187], v[234:237], v[96:99]
	v_mfma_f32_16x16x32_bf16 v[84:87], v[164:167], v[242:245], v[84:87]
	v_mfma_f32_16x16x32_bf16 v[80:83], v[184:187], v[242:245], v[80:83]
	s_setprio 0
	s_setprio 1
	v_mfma_f32_16x16x32_bf16 v[124:127], v[188:191], v[214:217], v[124:127]
	v_mfma_f32_16x16x32_bf16 v[120:123], v[196:199], v[214:217], v[120:123]
	v_mfma_f32_16x16x32_bf16 v[108:111], v[188:191], v[222:225], v[108:111]
	v_mfma_f32_16x16x32_bf16 v[104:107], v[196:199], v[222:225], v[104:107]
	v_mfma_f32_16x16x32_bf16 v[92:95], v[188:191], v[230:233], v[92:95]
	v_mfma_f32_16x16x32_bf16 v[88:91], v[196:199], v[230:233], v[88:91]
	v_mfma_f32_16x16x32_bf16 v[76:79], v[188:191], v[238:241], v[76:79]
	v_mfma_f32_16x16x32_bf16 v[72:75], v[196:199], v[238:241], v[72:75]
	v_mfma_f32_16x16x32_bf16 v[124:127], v[192:195], v[218:221], v[124:127]
	v_mfma_f32_16x16x32_bf16 v[120:123], v[200:203], v[218:221], v[120:123]
	v_mfma_f32_16x16x32_bf16 v[108:111], v[192:195], v[226:229], v[108:111]
	v_mfma_f32_16x16x32_bf16 v[104:107], v[200:203], v[226:229], v[104:107]
	v_mfma_f32_16x16x32_bf16 v[92:95], v[192:195], v[234:237], v[92:95]
	v_mfma_f32_16x16x32_bf16 v[88:91], v[200:203], v[234:237], v[88:91]
	v_mfma_f32_16x16x32_bf16 v[76:79], v[192:195], v[242:245], v[76:79]
	v_mfma_f32_16x16x32_bf16 v[72:75], v[200:203], v[242:245], v[72:75]
	s_setprio 0
	s_barrier
	ds_read_b128 v[214:217], v173 offset:49152
	ds_read_b128 v[218:221], v173 offset:50176
	ds_read_b128 v[222:225], v173 offset:51200
	ds_read_b128 v[226:229], v173 offset:52224
	ds_read_b128 v[230:233], v173 offset:53248
	ds_read_b128 v[234:237], v173 offset:54272
	ds_read_b128 v[238:241], v173 offset:55296
	ds_read_b128 v[242:245], v173 offset:56320
	global_load_lds_dwordx4 v136, s[98:99]
	s_add_i32 m0, s42, 0x2000
	s_add_u32 s38, s38, 0x80080
	s_addc_u32 s39, s39, 0
	s_add_i32 s42, s47, s53
	global_load_lds_dwordx4 v140, s[98:99]
	s_mov_b32 m0, s42
	s_nop 0
	global_load_lds_dwordx4 v136, s[38:39]
	s_add_i32 m0, s42, 0x2000
	s_nop 0
	global_load_lds_dwordx4 v140, s[38:39]
	s_mov_b32 m0, s61
	s_nop 0
	global_load_lds_dwordx4 v14, s[100:101]
	s_mov_b32 m0, s64
	s_nop 0
	global_load_lds_dwordx4 v138, s[100:101]
	s_waitcnt vmcnt(8)
	s_waitcnt lgkmcnt(0)
	s_barrier
	s_setprio 1
	s_waitcnt lgkmcnt(0)
	v_mfma_f32_16x16x32_bf16 v[68:71], v[160:163], v[214:217], v[68:71]
	v_mfma_f32_16x16x32_bf16 v[64:67], v[174:177], v[214:217], v[64:67]
	v_mfma_f32_16x16x32_bf16 v[52:55], v[160:163], v[222:225], v[52:55]
	s_add_i32 s27, s27, 2
	v_mfma_f32_16x16x32_bf16 v[48:51], v[174:177], v[222:225], v[48:51]
	s_add_u32 s36, s36, 0x100
	v_mfma_f32_16x16x32_bf16 v[36:39], v[160:163], v[230:233], v[36:39]
	s_addc_u32 s37, s37, 0
	v_mfma_f32_16x16x32_bf16 v[30:33], v[174:177], v[230:233], v[30:33]
	s_add_u32 s25, s25, 0x100
	v_mfma_f32_16x16x32_bf16 v[18:21], v[160:163], v[238:241], v[18:21]
	s_addc_u32 s26, s26, 0
	v_mfma_f32_16x16x32_bf16 v[10:13], v[174:177], v[238:241], v[10:13]
	v_mfma_f32_16x16x32_bf16 v[68:71], v[164:167], v[218:221], v[68:71]
	v_mfma_f32_16x16x32_bf16 v[64:67], v[184:187], v[218:221], v[64:67]
	v_mfma_f32_16x16x32_bf16 v[52:55], v[164:167], v[226:229], v[52:55]
	v_mfma_f32_16x16x32_bf16 v[48:51], v[184:187], v[226:229], v[48:51]
	v_mfma_f32_16x16x32_bf16 v[36:39], v[164:167], v[234:237], v[36:39]
	v_mfma_f32_16x16x32_bf16 v[30:33], v[184:187], v[234:237], v[30:33]
	v_mfma_f32_16x16x32_bf16 v[18:21], v[164:167], v[242:245], v[18:21]
	v_mfma_f32_16x16x32_bf16 v[10:13], v[184:187], v[242:245], v[10:13]
	s_setprio 0
	s_setprio 1
	v_mfma_f32_16x16x32_bf16 v[60:63], v[188:191], v[214:217], v[60:63]
	v_mfma_f32_16x16x32_bf16 v[56:59], v[196:199], v[214:217], v[56:59]
	v_mfma_f32_16x16x32_bf16 v[44:47], v[188:191], v[222:225], v[44:47]
	v_mfma_f32_16x16x32_bf16 v[40:43], v[196:199], v[222:225], v[40:43]
	v_mfma_f32_16x16x32_bf16 v[26:29], v[188:191], v[230:233], v[26:29]
	v_mfma_f32_16x16x32_bf16 v[22:25], v[196:199], v[230:233], v[22:25]
	v_mfma_f32_16x16x32_bf16 v[6:9], v[188:191], v[238:241], v[6:9]
	v_mfma_f32_16x16x32_bf16 v[2:5], v[196:199], v[238:241], v[2:5]
	v_mfma_f32_16x16x32_bf16 v[60:63], v[192:195], v[218:221], v[60:63]
	v_mfma_f32_16x16x32_bf16 v[56:59], v[200:203], v[218:221], v[56:59]
	v_mfma_f32_16x16x32_bf16 v[44:47], v[192:195], v[226:229], v[44:47]
	v_mfma_f32_16x16x32_bf16 v[40:43], v[200:203], v[226:229], v[40:43]
	v_mfma_f32_16x16x32_bf16 v[26:29], v[192:195], v[234:237], v[26:29]
	v_mfma_f32_16x16x32_bf16 v[22:25], v[200:203], v[234:237], v[22:25]
	v_mfma_f32_16x16x32_bf16 v[6:9], v[192:195], v[242:245], v[6:9]
	v_mfma_f32_16x16x32_bf16 v[2:5], v[200:203], v[242:245], v[2:5]
	s_setprio 0
	s_barrier
	s_cmp_gt_u32 s27, 29
	s_cbranch_scc0 .LBB0_306
	s_and_b64 vcc, exec, s[28:29]
	s_cbranch_vccz .LBB0_309
	s_barrier

.LBB0_1124:
	s_add_i32 vcc_lo, s44, 2
	s_add_u32 s38, s8, 0x100
	s_addc_u32 s39, s9, 0
	s_add_i32 s72, 0, 0x10000
	s_cmp_eq_u32 s29, s44
	s_cselect_b32 s47, s35, s39
	s_cselect_b32 s46, s34, s38
	v_add_u32_e32 v34, s72, v183
	s_cselect_b32 s45, s49, s71
	s_cselect_b32 s44, s48, s70
	s_add_i32 s73, 0, 0x14000
	ds_read_b128 v[42:45], v34
	ds_read_b128 v[46:49], v34 offset:1024
	ds_read_b128 v[74:77], v34 offset:2048
	ds_read_b128 v[78:81], v34 offset:3072
	v_add_u32_e32 v34, s73, v183
	ds_read_b128 v[106:109], v34
	ds_read_b128 v[110:113], v34 offset:1024
	ds_read_b128 v[138:141], v34 offset:2048
	ds_read_b128 v[142:145], v34 offset:3072
	s_add_i32 m0, s25, 0xc000
	ds_read_b128 v[170:173], v205
	ds_read_b128 v[174:177], v205 offset:1024
	ds_read_b128 v[196:199], v205 offset:2048
	ds_read_b128 v[200:203], v205 offset:3072
	ds_read_b128 v[214:217], v205 offset:4096
	ds_read_b128 v[218:221], v205 offset:5120
	ds_read_b128 v[222:225], v205 offset:6144
	ds_read_b128 v[226:229], v205 offset:7168
	global_load_lds_dwordx4 v192, s[8:9]
	s_add_i32 m0, s25, 0xe000
	s_nop 0
	global_load_lds_dwordx4 v194, s[8:9]
	s_waitcnt vmcnt(8)
	s_waitcnt lgkmcnt(0)
	s_barrier
	s_setprio 1
	s_waitcnt lgkmcnt(0)
	v_mfma_f32_16x16x32_bf16 v[62:65], v[42:45], v[170:173], v[62:65]
	v_mfma_f32_16x16x32_bf16 v[58:61], v[74:77], v[170:173], v[58:61]
	v_mfma_f32_16x16x32_bf16 v[94:97], v[42:45], v[196:199], v[94:97]
	s_add_u32 s98, s44, s22
	v_mfma_f32_16x16x32_bf16 v[90:93], v[74:77], v[196:199], v[90:93]
	s_addc_u32 s99, s45, s23
	v_mfma_f32_16x16x32_bf16 v[118:121], v[42:45], v[214:217], v[118:121]
	s_add_u32 s100, s46, s22
	v_mfma_f32_16x16x32_bf16 v[114:117], v[74:77], v[214:217], v[114:117]
	s_addc_u32 s101, s47, s23
	v_mfma_f32_16x16x32_bf16 v[134:137], v[42:45], v[222:225], v[134:137]
	s_add_i32 s8, s72, s20
	v_mfma_f32_16x16x32_bf16 v[130:133], v[74:77], v[222:225], v[130:133]
	s_mov_b32 m0, s8
	v_mfma_f32_16x16x32_bf16 v[62:65], v[46:49], v[174:177], v[62:65]
	v_mfma_f32_16x16x32_bf16 v[58:61], v[78:81], v[174:177], v[58:61]
	v_mfma_f32_16x16x32_bf16 v[94:97], v[46:49], v[200:203], v[94:97]
	v_mfma_f32_16x16x32_bf16 v[90:93], v[78:81], v[200:203], v[90:93]
	v_mfma_f32_16x16x32_bf16 v[118:121], v[46:49], v[218:221], v[118:121]
	v_mfma_f32_16x16x32_bf16 v[114:117], v[78:81], v[218:221], v[114:117]
	v_mfma_f32_16x16x32_bf16 v[134:137], v[46:49], v[226:229], v[134:137]
	v_mfma_f32_16x16x32_bf16 v[130:133], v[78:81], v[226:229], v[130:133]
	s_setprio 0
	s_setprio 1
	v_mfma_f32_16x16x32_bf16 v[166:169], v[106:109], v[170:173], v[166:169]
	v_mfma_f32_16x16x32_bf16 v[162:165], v[138:141], v[170:173], v[162:165]
	v_mfma_f32_16x16x32_bf16 v[158:161], v[106:109], v[196:199], v[158:161]
	v_mfma_f32_16x16x32_bf16 v[154:157], v[138:141], v[196:199], v[154:157]
	v_mfma_f32_16x16x32_bf16 v[150:153], v[106:109], v[214:217], v[150:153]
	v_mfma_f32_16x16x32_bf16 v[146:149], v[138:141], v[214:217], v[146:149]
	v_mfma_f32_16x16x32_bf16 v[126:129], v[106:109], v[222:225], v[126:129]
	v_mfma_f32_16x16x32_bf16 v[122:125], v[138:141], v[222:225], v[122:125]
	v_mfma_f32_16x16x32_bf16 v[166:169], v[110:113], v[174:177], v[166:169]
	v_mfma_f32_16x16x32_bf16 v[162:165], v[142:145], v[174:177], v[162:165]
	v_mfma_f32_16x16x32_bf16 v[158:161], v[110:113], v[200:203], v[158:161]
	v_mfma_f32_16x16x32_bf16 v[154:157], v[142:145], v[200:203], v[154:157]
	v_mfma_f32_16x16x32_bf16 v[150:153], v[110:113], v[218:221], v[150:153]
	v_mfma_f32_16x16x32_bf16 v[146:149], v[142:145], v[218:221], v[146:149]
	v_mfma_f32_16x16x32_bf16 v[126:129], v[110:113], v[226:229], v[126:129]
	v_mfma_f32_16x16x32_bf16 v[122:125], v[142:145], v[226:229], v[122:125]
	s_setprio 0
	s_barrier
	ds_read_b128 v[170:173], v205 offset:16384
	ds_read_b128 v[174:177], v205 offset:17408
	ds_read_b128 v[196:199], v205 offset:18432
	ds_read_b128 v[200:203], v205 offset:19456
	ds_read_b128 v[214:217], v205 offset:20480
	ds_read_b128 v[218:221], v205 offset:21504
	ds_read_b128 v[222:225], v205 offset:22528
	ds_read_b128 v[226:229], v205 offset:23552
	global_load_lds_dwordx4 v184, s[44:45]
	s_add_i32 m0, s8, 0x2000
	s_add_u32 s8, s44, 0xc0000
	s_addc_u32 s9, s45, 0
	s_add_i32 s72, s73, s20
	global_load_lds_dwordx4 v188, s[44:45]
	s_mov_b32 m0, s72
	s_nop 0
	global_load_lds_dwordx4 v184, s[8:9]
	s_add_i32 m0, s72, 0x2000
	s_nop 0
	global_load_lds_dwordx4 v188, s[8:9]
	s_mov_b32 m0, s25
	s_nop 0
	global_load_lds_dwordx4 v14, s[46:47]
	s_mov_b32 m0, s26
	s_nop 0
	global_load_lds_dwordx4 v186, s[46:47]
	s_waitcnt vmcnt(8)
	s_waitcnt lgkmcnt(0)
	s_barrier
	s_setprio 1
	s_waitcnt lgkmcnt(0)
	v_mfma_f32_16x16x32_bf16 v[102:105], v[42:45], v[170:173], v[102:105]
	v_mfma_f32_16x16x32_bf16 v[98:101], v[74:77], v[170:173], v[98:101]
	v_mfma_f32_16x16x32_bf16 v[70:73], v[42:45], v[196:199], v[70:73]
	s_add_i32 s72, 0, 0x18000
	v_mfma_f32_16x16x32_bf16 v[66:69], v[74:77], v[196:199], v[66:69]
	v_mfma_f32_16x16x32_bf16 v[36:39], v[42:45], v[214:217], v[38:41]
	v_mfma_f32_16x16x32_bf16 v[30:33], v[74:77], v[214:217], v[30:33]
	v_mfma_f32_16x16x32_bf16 v[18:21], v[42:45], v[222:225], v[18:21]
	v_mfma_f32_16x16x32_bf16 v[10:13], v[74:77], v[222:225], v[10:13]
	v_mfma_f32_16x16x32_bf16 v[102:105], v[46:49], v[174:177], v[102:105]
	v_mfma_f32_16x16x32_bf16 v[98:101], v[78:81], v[174:177], v[98:101]
	v_mfma_f32_16x16x32_bf16 v[70:73], v[46:49], v[200:203], v[70:73]
	v_mfma_f32_16x16x32_bf16 v[66:69], v[78:81], v[200:203], v[66:69]
	v_mfma_f32_16x16x32_bf16 v[36:39], v[46:49], v[218:221], v[36:39]
	v_mfma_f32_16x16x32_bf16 v[30:33], v[78:81], v[218:221], v[30:33]
	v_mfma_f32_16x16x32_bf16 v[18:21], v[46:49], v[226:229], v[18:21]
	v_mfma_f32_16x16x32_bf16 v[10:13], v[78:81], v[226:229], v[10:13]
	s_setprio 0
	s_setprio 1
	v_mfma_f32_16x16x32_bf16 v[54:57], v[106:109], v[196:199], v[54:57]
	v_mfma_f32_16x16x32_bf16 v[50:53], v[138:141], v[196:199], v[50:53]
	v_mfma_f32_16x16x32_bf16 v[26:29], v[106:109], v[214:217], v[26:29]
	v_mfma_f32_16x16x32_bf16 v[22:25], v[138:141], v[214:217], v[22:25]
	v_mfma_f32_16x16x32_bf16 v[6:9], v[106:109], v[222:225], v[6:9]
	v_mfma_f32_16x16x32_bf16 v[2:5], v[138:141], v[222:225], v[2:5]
	v_mfma_f32_16x16x32_bf16 v[40:43], v[106:109], v[170:173], v[86:89]
	v_mfma_f32_16x16x32_bf16 v[46:49], v[138:141], v[170:173], v[82:85]
	v_mfma_f32_16x16x32_bf16 v[54:57], v[110:113], v[200:203], v[54:57]
	v_mfma_f32_16x16x32_bf16 v[50:53], v[142:145], v[200:203], v[50:53]
	v_mfma_f32_16x16x32_bf16 v[26:29], v[110:113], v[218:221], v[26:29]
	v_mfma_f32_16x16x32_bf16 v[22:25], v[142:145], v[218:221], v[22:25]
	v_mfma_f32_16x16x32_bf16 v[6:9], v[110:113], v[226:229], v[6:9]
	v_mfma_f32_16x16x32_bf16 v[2:5], v[142:145], v[226:229], v[2:5]
	v_mfma_f32_16x16x32_bf16 v[42:45], v[110:113], v[174:177], v[40:43]
	v_mfma_f32_16x16x32_bf16 v[46:49], v[142:145], v[174:177], v[46:49]
	s_setprio 0
	s_barrier
	v_add_u32_e32 v34, s72, v183
	s_add_i32 s73, 0, 0x1c000
	ds_read_b128 v[74:77], v34
	ds_read_b128 v[78:81], v34 offset:1024
	ds_read_b128 v[82:85], v34 offset:2048
	ds_read_b128 v[86:89], v34 offset:3072
	v_add_u32_e32 v34, s73, v183
	ds_read_b128 v[106:109], v34
	ds_read_b128 v[110:113], v34 offset:1024
	ds_read_b128 v[138:141], v34 offset:2048
	ds_read_b128 v[142:145], v34 offset:3072
	s_add_u32 s8, s46, 0xc0000
	s_addc_u32 s9, s47, 0
	s_mov_b32 m0, s27
	ds_read_b128 v[170:173], v205 offset:32768
	ds_read_b128 v[174:177], v205 offset:33792
	ds_read_b128 v[196:199], v205 offset:34816
	ds_read_b128 v[200:203], v205 offset:35840
	ds_read_b128 v[214:217], v205 offset:36864
	ds_read_b128 v[218:221], v205 offset:37888
	ds_read_b128 v[222:225], v205 offset:38912
	ds_read_b128 v[226:229], v205 offset:39936
	global_load_lds_dwordx4 v14, s[8:9]
	s_mov_b32 m0, s31
	s_nop 0
	global_load_lds_dwordx4 v186, s[8:9]
	s_waitcnt vmcnt(8)
	s_waitcnt lgkmcnt(0)
	s_barrier
	s_setprio 1
	s_waitcnt lgkmcnt(0)
	v_mfma_f32_16x16x32_bf16 v[62:65], v[74:77], v[170:173], v[62:65]
	v_mfma_f32_16x16x32_bf16 v[58:61], v[82:85], v[170:173], v[58:61]
	v_mfma_f32_16x16x32_bf16 v[94:97], v[74:77], v[196:199], v[94:97]
	s_add_i32 s8, s72, s20
	v_mfma_f32_16x16x32_bf16 v[90:93], v[82:85], v[196:199], v[90:93]
	s_mov_b32 m0, s8
	v_mfma_f32_16x16x32_bf16 v[118:121], v[74:77], v[214:217], v[118:121]
	v_mfma_f32_16x16x32_bf16 v[114:117], v[82:85], v[214:217], v[114:117]
	v_mfma_f32_16x16x32_bf16 v[134:137], v[74:77], v[222:225], v[134:137]
	v_mfma_f32_16x16x32_bf16 v[130:133], v[82:85], v[222:225], v[130:133]
	v_mfma_f32_16x16x32_bf16 v[62:65], v[78:81], v[174:177], v[62:65]
	v_mfma_f32_16x16x32_bf16 v[58:61], v[86:89], v[174:177], v[58:61]
	v_mfma_f32_16x16x32_bf16 v[94:97], v[78:81], v[200:203], v[94:97]
	v_mfma_f32_16x16x32_bf16 v[90:93], v[86:89], v[200:203], v[90:93]
	v_mfma_f32_16x16x32_bf16 v[118:121], v[78:81], v[218:221], v[118:121]
	v_mfma_f32_16x16x32_bf16 v[114:117], v[86:89], v[218:221], v[114:117]
	v_mfma_f32_16x16x32_bf16 v[134:137], v[78:81], v[226:229], v[134:137]
	v_mfma_f32_16x16x32_bf16 v[130:133], v[86:89], v[226:229], v[130:133]
	s_setprio 0
	s_setprio 1
	v_mfma_f32_16x16x32_bf16 v[166:169], v[106:109], v[170:173], v[166:169]
	v_mfma_f32_16x16x32_bf16 v[162:165], v[138:141], v[170:173], v[162:165]
	v_mfma_f32_16x16x32_bf16 v[158:161], v[106:109], v[196:199], v[158:161]
	v_mfma_f32_16x16x32_bf16 v[154:157], v[138:141], v[196:199], v[154:157]
	v_mfma_f32_16x16x32_bf16 v[150:153], v[106:109], v[214:217], v[150:153]
	v_mfma_f32_16x16x32_bf16 v[146:149], v[138:141], v[214:217], v[146:149]
	v_mfma_f32_16x16x32_bf16 v[126:129], v[106:109], v[222:225], v[126:129]
	v_mfma_f32_16x16x32_bf16 v[122:125], v[138:141], v[222:225], v[122:125]
	v_mfma_f32_16x16x32_bf16 v[166:169], v[110:113], v[174:177], v[166:169]
	v_mfma_f32_16x16x32_bf16 v[162:165], v[142:145], v[174:177], v[162:165]
	v_mfma_f32_16x16x32_bf16 v[158:161], v[110:113], v[200:203], v[158:161]
	v_mfma_f32_16x16x32_bf16 v[154:157], v[142:145], v[200:203], v[154:157]
	v_mfma_f32_16x16x32_bf16 v[150:153], v[110:113], v[218:221], v[150:153]
	v_mfma_f32_16x16x32_bf16 v[146:149], v[142:145], v[218:221], v[146:149]
	v_mfma_f32_16x16x32_bf16 v[126:129], v[110:113], v[226:229], v[126:129]
	v_mfma_f32_16x16x32_bf16 v[122:125], v[142:145], v[226:229], v[122:125]
	s_setprio 0
	s_barrier
	ds_read_b128 v[170:173], v205 offset:49152
	ds_read_b128 v[174:177], v205 offset:50176
	ds_read_b128 v[196:199], v205 offset:51200
	ds_read_b128 v[200:203], v205 offset:52224
	ds_read_b128 v[214:217], v205 offset:53248
	ds_read_b128 v[218:221], v205 offset:54272
	ds_read_b128 v[222:225], v205 offset:55296
	ds_read_b128 v[226:229], v205 offset:56320
	global_load_lds_dwordx4 v184, s[98:99]
	s_add_i32 m0, s8, 0x2000
	s_add_u32 s8, s44, 0xc0080
	s_addc_u32 s9, s45, 0
	s_add_i32 s44, s73, s20
	global_load_lds_dwordx4 v188, s[98:99]
	s_mov_b32 m0, s44
	s_nop 0
	global_load_lds_dwordx4 v184, s[8:9]
	s_add_i32 m0, s44, 0x2000
	s_nop 0
	global_load_lds_dwordx4 v188, s[8:9]
	s_mov_b32 m0, s52
	s_nop 0
	global_load_lds_dwordx4 v14, s[100:101]
	s_mov_b32 m0, s53
	s_nop 0
	global_load_lds_dwordx4 v186, s[100:101]
	s_waitcnt vmcnt(8)
	s_waitcnt lgkmcnt(0)
	s_barrier
	s_setprio 1
	s_waitcnt lgkmcnt(0)
	v_mfma_f32_16x16x32_bf16 v[102:105], v[74:77], v[170:173], v[102:105]
	v_mfma_f32_16x16x32_bf16 v[98:101], v[82:85], v[170:173], v[98:101]
	v_mfma_f32_16x16x32_bf16 v[70:73], v[74:77], v[196:199], v[70:73]
	s_add_u32 s70, s70, 0x100
	v_mfma_f32_16x16x32_bf16 v[66:69], v[82:85], v[196:199], v[66:69]
	s_addc_u32 s71, s71, 0
	v_mfma_f32_16x16x32_bf16 v[36:39], v[74:77], v[214:217], v[36:39]
	v_mfma_f32_16x16x32_bf16 v[30:33], v[82:85], v[214:217], v[30:33]
	v_mfma_f32_16x16x32_bf16 v[18:21], v[74:77], v[222:225], v[18:21]
	v_mfma_f32_16x16x32_bf16 v[10:13], v[82:85], v[222:225], v[10:13]
	v_mfma_f32_16x16x32_bf16 v[102:105], v[78:81], v[174:177], v[102:105]
	v_mfma_f32_16x16x32_bf16 v[98:101], v[86:89], v[174:177], v[98:101]
	v_mfma_f32_16x16x32_bf16 v[70:73], v[78:81], v[200:203], v[70:73]
	v_mfma_f32_16x16x32_bf16 v[66:69], v[86:89], v[200:203], v[66:69]
	v_mfma_f32_16x16x32_bf16 v[38:41], v[78:81], v[218:221], v[36:39]
	v_mfma_f32_16x16x32_bf16 v[30:33], v[86:89], v[218:221], v[30:33]
	v_mfma_f32_16x16x32_bf16 v[18:21], v[78:81], v[226:229], v[18:21]
	v_mfma_f32_16x16x32_bf16 v[10:13], v[86:89], v[226:229], v[10:13]
	s_setprio 0
	s_setprio 1
	v_mfma_f32_16x16x32_bf16 v[42:45], v[106:109], v[170:173], v[42:45]
	v_mfma_f32_16x16x32_bf16 v[86:89], v[110:113], v[174:177], v[42:45]
	v_mfma_f32_16x16x32_bf16 v[42:45], v[138:141], v[170:173], v[46:49]
	v_mfma_f32_16x16x32_bf16 v[82:85], v[142:145], v[174:177], v[42:45]
	v_mfma_f32_16x16x32_bf16 v[42:45], v[106:109], v[196:199], v[54:57]
	v_mfma_f32_16x16x32_bf16 v[54:57], v[110:113], v[200:203], v[42:45]
	v_mfma_f32_16x16x32_bf16 v[42:45], v[138:141], v[196:199], v[50:53]
	v_mfma_f32_16x16x32_bf16 v[26:29], v[106:109], v[214:217], v[26:29]
	v_mfma_f32_16x16x32_bf16 v[22:25], v[138:141], v[214:217], v[22:25]
	v_mfma_f32_16x16x32_bf16 v[6:9], v[106:109], v[222:225], v[6:9]
	v_mfma_f32_16x16x32_bf16 v[2:5], v[138:141], v[222:225], v[2:5]
	v_mfma_f32_16x16x32_bf16 v[50:53], v[142:145], v[200:203], v[42:45]
	v_mfma_f32_16x16x32_bf16 v[26:29], v[110:113], v[218:221], v[26:29]
	v_mfma_f32_16x16x32_bf16 v[22:25], v[142:145], v[218:221], v[22:25]
	v_mfma_f32_16x16x32_bf16 v[6:9], v[110:113], v[226:229], v[6:9]
	v_mfma_f32_16x16x32_bf16 v[2:5], v[142:145], v[226:229], v[2:5]
	s_setprio 0
	s_barrier
	s_cmp_ge_i32 vcc_lo, s51
	s_mov_b64 s[8:9], s[38:39]
	s_mov_b32 s44, vcc_lo
	s_cbranch_scc0 .LBB0_1124
	s_and_b64 vcc, exec, s[12:13]
	s_cbranch_vccz .LBB0_1127
	s_barrier

.LBB0_1508:
	s_add_i32 s39, s35, 2
	s_add_u32 s50, s48, 0xfff80080
	s_addc_u32 s51, s49, -1
	s_add_i32 s72, 0, 0x10000
	s_cmp_eq_u32 s9, s35
	s_cselect_b32 s53, s37, s51
	s_cselect_b32 s52, s36, s50
	s_cselect_b32 s51, s45, s29
	s_cselect_b32 s50, s44, s13
	s_add_i32 s35, 0, 0x14000
	v_add_u32_e32 v160, s72, v152
	v_add_u32_e32 v176, s35, v152
	ds_read_b128 v[136:139], v160
	ds_read_b128 v[148:151], v160 offset:1024
	ds_read_b128 v[156:159], v160 offset:2048
	ds_read_b128 v[160:163], v160 offset:3072
	ds_read_b128 v[164:167], v176
	ds_read_b128 v[168:171], v176 offset:1024
	ds_read_b128 v[172:175], v176 offset:2048
	ds_read_b128 v[184:187], v176 offset:3072
	s_add_i32 m0, s25, 0xc000
	ds_read_b128 v[188:191], v155
	ds_read_b128 v[192:195], v155 offset:1024
	ds_read_b128 v[196:199], v155 offset:2048
	ds_read_b128 v[200:203], v155 offset:3072
	ds_read_b128 v[214:217], v155 offset:4096
	ds_read_b128 v[218:221], v155 offset:5120
	ds_read_b128 v[222:225], v155 offset:6144
	ds_read_b128 v[226:229], v155 offset:7168
	global_load_lds_dwordx4 v144, s[48:49]
	s_add_i32 m0, s25, 0xe000
	s_nop 0
	global_load_lds_dwordx4 v146, s[48:49]
	s_waitcnt vmcnt(8)
	s_waitcnt lgkmcnt(0)
	s_barrier
	s_setprio 1
	s_waitcnt lgkmcnt(0)
	v_mfma_f32_16x16x32_bf16 v[132:135], v[136:139], v[188:191], v[132:135]
	v_mfma_f32_16x16x32_bf16 v[128:131], v[156:159], v[188:191], v[128:131]
	v_mfma_f32_16x16x32_bf16 v[116:119], v[136:139], v[196:199], v[116:119]
	s_add_u32 s98, s50, s22
	v_mfma_f32_16x16x32_bf16 v[112:115], v[156:159], v[196:199], v[112:115]
	s_addc_u32 s99, s51, s23
	v_mfma_f32_16x16x32_bf16 v[100:103], v[136:139], v[214:217], v[100:103]
	s_add_u32 s100, s52, s22
	v_mfma_f32_16x16x32_bf16 v[96:99], v[156:159], v[214:217], v[96:99]
	s_addc_u32 s101, s53, s23
	v_mfma_f32_16x16x32_bf16 v[84:87], v[136:139], v[222:225], v[84:87]
	s_add_i32 s72, s72, s20
	v_mfma_f32_16x16x32_bf16 v[80:83], v[156:159], v[222:225], v[80:83]
	s_mov_b32 m0, s72
	v_mfma_f32_16x16x32_bf16 v[132:135], v[148:151], v[192:195], v[132:135]
	v_mfma_f32_16x16x32_bf16 v[128:131], v[160:163], v[192:195], v[128:131]
	v_mfma_f32_16x16x32_bf16 v[116:119], v[148:151], v[200:203], v[116:119]
	v_mfma_f32_16x16x32_bf16 v[112:115], v[160:163], v[200:203], v[112:115]
	v_mfma_f32_16x16x32_bf16 v[100:103], v[148:151], v[218:221], v[100:103]
	v_mfma_f32_16x16x32_bf16 v[96:99], v[160:163], v[218:221], v[96:99]
	v_mfma_f32_16x16x32_bf16 v[84:87], v[148:151], v[226:229], v[84:87]
	v_mfma_f32_16x16x32_bf16 v[80:83], v[160:163], v[226:229], v[80:83]
	s_setprio 0
	s_setprio 1
	v_mfma_f32_16x16x32_bf16 v[124:127], v[164:167], v[188:191], v[124:127]
	v_mfma_f32_16x16x32_bf16 v[120:123], v[172:175], v[188:191], v[120:123]
	v_mfma_f32_16x16x32_bf16 v[108:111], v[164:167], v[196:199], v[108:111]
	v_mfma_f32_16x16x32_bf16 v[104:107], v[172:175], v[196:199], v[104:107]
	v_mfma_f32_16x16x32_bf16 v[92:95], v[164:167], v[214:217], v[92:95]
	v_mfma_f32_16x16x32_bf16 v[88:91], v[172:175], v[214:217], v[88:91]
	v_mfma_f32_16x16x32_bf16 v[76:79], v[164:167], v[222:225], v[76:79]
	v_mfma_f32_16x16x32_bf16 v[72:75], v[172:175], v[222:225], v[72:75]
	v_mfma_f32_16x16x32_bf16 v[124:127], v[168:171], v[192:195], v[124:127]
	v_mfma_f32_16x16x32_bf16 v[120:123], v[184:187], v[192:195], v[120:123]
	v_mfma_f32_16x16x32_bf16 v[108:111], v[168:171], v[200:203], v[108:111]
	v_mfma_f32_16x16x32_bf16 v[104:107], v[184:187], v[200:203], v[104:107]
	v_mfma_f32_16x16x32_bf16 v[92:95], v[168:171], v[218:221], v[92:95]
	v_mfma_f32_16x16x32_bf16 v[88:91], v[184:187], v[218:221], v[88:91]
	v_mfma_f32_16x16x32_bf16 v[76:79], v[168:171], v[226:229], v[76:79]
	v_mfma_f32_16x16x32_bf16 v[72:75], v[184:187], v[226:229], v[72:75]
	s_setprio 0
	s_barrier
	ds_read_b128 v[188:191], v155 offset:16384
	ds_read_b128 v[192:195], v155 offset:17408
	ds_read_b128 v[196:199], v155 offset:18432
	ds_read_b128 v[200:203], v155 offset:19456
	ds_read_b128 v[214:217], v155 offset:20480
	ds_read_b128 v[218:221], v155 offset:21504
	ds_read_b128 v[222:225], v155 offset:22528
	ds_read_b128 v[226:229], v155 offset:23552
	global_load_lds_dwordx4 v34, s[50:51]
	s_add_i32 m0, s72, 0x2000
	s_add_u32 s72, s50, 0x80000
	s_addc_u32 s73, s51, 0
	s_add_i32 s35, s35, s20
	global_load_lds_dwordx4 v142, s[50:51]
	s_mov_b32 m0, s35
	s_nop 0
	global_load_lds_dwordx4 v34, s[72:73]
	s_add_i32 m0, s35, 0x2000
	s_nop 0
	global_load_lds_dwordx4 v142, s[72:73]
	s_mov_b32 m0, s25
	s_nop 0
	global_load_lds_dwordx4 v14, s[52:53]
	s_mov_b32 m0, s26
	s_nop 0
	global_load_lds_dwordx4 v140, s[52:53]
	s_waitcnt vmcnt(8)
	s_waitcnt lgkmcnt(0)
	s_barrier
	s_setprio 1
	s_waitcnt lgkmcnt(0)
	v_mfma_f32_16x16x32_bf16 v[68:71], v[136:139], v[188:191], v[68:71]
	v_mfma_f32_16x16x32_bf16 v[64:67], v[156:159], v[188:191], v[64:67]
	v_mfma_f32_16x16x32_bf16 v[52:55], v[136:139], v[196:199], v[52:55]
	s_add_i32 s35, 0, 0x18000
	v_mfma_f32_16x16x32_bf16 v[48:51], v[156:159], v[196:199], v[48:51]
	s_add_i32 s72, 0, 0x1c000
	v_mfma_f32_16x16x32_bf16 v[36:39], v[136:139], v[214:217], v[36:39]
	v_mfma_f32_16x16x32_bf16 v[30:33], v[156:159], v[214:217], v[30:33]
	v_mfma_f32_16x16x32_bf16 v[18:21], v[136:139], v[222:225], v[18:21]
	v_mfma_f32_16x16x32_bf16 v[10:13], v[156:159], v[222:225], v[10:13]
	v_mfma_f32_16x16x32_bf16 v[68:71], v[148:151], v[192:195], v[68:71]
	v_mfma_f32_16x16x32_bf16 v[64:67], v[160:163], v[192:195], v[64:67]
	v_mfma_f32_16x16x32_bf16 v[52:55], v[148:151], v[200:203], v[52:55]
	v_mfma_f32_16x16x32_bf16 v[48:51], v[160:163], v[200:203], v[48:51]
	v_mfma_f32_16x16x32_bf16 v[36:39], v[148:151], v[218:221], v[36:39]
	v_mfma_f32_16x16x32_bf16 v[30:33], v[160:163], v[218:221], v[30:33]
	v_mfma_f32_16x16x32_bf16 v[18:21], v[148:151], v[226:229], v[18:21]
	v_mfma_f32_16x16x32_bf16 v[10:13], v[160:163], v[226:229], v[10:13]
	s_setprio 0
	s_setprio 1
	v_mfma_f32_16x16x32_bf16 v[60:63], v[164:167], v[188:191], v[60:63]
	v_mfma_f32_16x16x32_bf16 v[56:59], v[172:175], v[188:191], v[56:59]
	v_mfma_f32_16x16x32_bf16 v[44:47], v[164:167], v[196:199], v[44:47]
	v_mfma_f32_16x16x32_bf16 v[40:43], v[172:175], v[196:199], v[40:43]
	v_mfma_f32_16x16x32_bf16 v[26:29], v[164:167], v[214:217], v[26:29]
	v_mfma_f32_16x16x32_bf16 v[22:25], v[172:175], v[214:217], v[22:25]
	v_mfma_f32_16x16x32_bf16 v[6:9], v[164:167], v[222:225], v[6:9]
	v_mfma_f32_16x16x32_bf16 v[2:5], v[172:175], v[222:225], v[2:5]
	v_mfma_f32_16x16x32_bf16 v[60:63], v[168:171], v[192:195], v[60:63]
	v_mfma_f32_16x16x32_bf16 v[56:59], v[184:187], v[192:195], v[56:59]
	v_mfma_f32_16x16x32_bf16 v[44:47], v[168:171], v[200:203], v[44:47]
	v_mfma_f32_16x16x32_bf16 v[40:43], v[184:187], v[200:203], v[40:43]
	v_mfma_f32_16x16x32_bf16 v[26:29], v[168:171], v[218:221], v[26:29]
	v_mfma_f32_16x16x32_bf16 v[22:25], v[184:187], v[218:221], v[22:25]
	v_mfma_f32_16x16x32_bf16 v[6:9], v[168:171], v[226:229], v[6:9]
	v_mfma_f32_16x16x32_bf16 v[2:5], v[184:187], v[226:229], v[2:5]
	s_setprio 0
	s_barrier
	v_add_u32_e32 v160, s35, v152
	v_add_u32_e32 v183, s72, v152
	ds_read_b128 v[136:139], v160
	ds_read_b128 v[148:151], v160 offset:1024
	ds_read_b128 v[156:159], v160 offset:2048
	ds_read_b128 v[160:163], v160 offset:3072
	ds_read_b128 v[164:167], v183
	ds_read_b128 v[168:171], v183 offset:1024
	ds_read_b128 v[172:175], v183 offset:2048
	ds_read_b128 v[184:187], v183 offset:3072
	s_add_u32 s52, s52, 0x80000
	s_addc_u32 s53, s53, 0
	s_mov_b32 m0, s27
	ds_read_b128 v[188:191], v155 offset:32768
	ds_read_b128 v[192:195], v155 offset:33792
	ds_read_b128 v[196:199], v155 offset:34816
	ds_read_b128 v[200:203], v155 offset:35840
	ds_read_b128 v[214:217], v155 offset:36864
	ds_read_b128 v[218:221], v155 offset:37888
	ds_read_b128 v[222:225], v155 offset:38912
	ds_read_b128 v[226:229], v155 offset:39936
	global_load_lds_dwordx4 v14, s[52:53]
	s_mov_b32 m0, s31
	s_nop 0
	global_load_lds_dwordx4 v140, s[52:53]
	s_waitcnt vmcnt(8)
	s_waitcnt lgkmcnt(0)
	s_barrier
	s_setprio 1
	s_waitcnt lgkmcnt(0)
	v_mfma_f32_16x16x32_bf16 v[132:135], v[136:139], v[188:191], v[132:135]
	v_mfma_f32_16x16x32_bf16 v[128:131], v[156:159], v[188:191], v[128:131]
	v_mfma_f32_16x16x32_bf16 v[116:119], v[136:139], v[196:199], v[116:119]
	s_add_i32 s35, s35, s20
	v_mfma_f32_16x16x32_bf16 v[112:115], v[156:159], v[196:199], v[112:115]
	s_mov_b32 m0, s35
	v_mfma_f32_16x16x32_bf16 v[100:103], v[136:139], v[214:217], v[100:103]
	v_mfma_f32_16x16x32_bf16 v[96:99], v[156:159], v[214:217], v[96:99]
	v_mfma_f32_16x16x32_bf16 v[84:87], v[136:139], v[222:225], v[84:87]
	v_mfma_f32_16x16x32_bf16 v[80:83], v[156:159], v[222:225], v[80:83]
	v_mfma_f32_16x16x32_bf16 v[132:135], v[148:151], v[192:195], v[132:135]
	v_mfma_f32_16x16x32_bf16 v[128:131], v[160:163], v[192:195], v[128:131]
	v_mfma_f32_16x16x32_bf16 v[116:119], v[148:151], v[200:203], v[116:119]
	v_mfma_f32_16x16x32_bf16 v[112:115], v[160:163], v[200:203], v[112:115]
	v_mfma_f32_16x16x32_bf16 v[100:103], v[148:151], v[218:221], v[100:103]
	v_mfma_f32_16x16x32_bf16 v[96:99], v[160:163], v[218:221], v[96:99]
	v_mfma_f32_16x16x32_bf16 v[84:87], v[148:151], v[226:229], v[84:87]
	v_mfma_f32_16x16x32_bf16 v[80:83], v[160:163], v[226:229], v[80:83]
	s_setprio 0
	s_setprio 1
	v_mfma_f32_16x16x32_bf16 v[124:127], v[164:167], v[188:191], v[124:127]
	v_mfma_f32_16x16x32_bf16 v[120:123], v[172:175], v[188:191], v[120:123]
	v_mfma_f32_16x16x32_bf16 v[108:111], v[164:167], v[196:199], v[108:111]
	v_mfma_f32_16x16x32_bf16 v[104:107], v[172:175], v[196:199], v[104:107]
	v_mfma_f32_16x16x32_bf16 v[92:95], v[164:167], v[214:217], v[92:95]
	v_mfma_f32_16x16x32_bf16 v[88:91], v[172:175], v[214:217], v[88:91]
	v_mfma_f32_16x16x32_bf16 v[76:79], v[164:167], v[222:225], v[76:79]
	v_mfma_f32_16x16x32_bf16 v[72:75], v[172:175], v[222:225], v[72:75]
	v_mfma_f32_16x16x32_bf16 v[124:127], v[168:171], v[192:195], v[124:127]
	v_mfma_f32_16x16x32_bf16 v[120:123], v[184:187], v[192:195], v[120:123]
	v_mfma_f32_16x16x32_bf16 v[108:111], v[168:171], v[200:203], v[108:111]
	v_mfma_f32_16x16x32_bf16 v[104:107], v[184:187], v[200:203], v[104:107]
	v_mfma_f32_16x16x32_bf16 v[92:95], v[168:171], v[218:221], v[92:95]
	v_mfma_f32_16x16x32_bf16 v[88:91], v[184:187], v[218:221], v[88:91]
	v_mfma_f32_16x16x32_bf16 v[76:79], v[168:171], v[226:229], v[76:79]
	v_mfma_f32_16x16x32_bf16 v[72:75], v[184:187], v[226:229], v[72:75]
	s_setprio 0
	s_barrier
	ds_read_b128 v[188:191], v155 offset:49152
	ds_read_b128 v[192:195], v155 offset:50176
	ds_read_b128 v[196:199], v155 offset:51200
	ds_read_b128 v[200:203], v155 offset:52224
	ds_read_b128 v[214:217], v155 offset:53248
	ds_read_b128 v[218:221], v155 offset:54272
	ds_read_b128 v[222:225], v155 offset:55296
	ds_read_b128 v[226:229], v155 offset:56320
	global_load_lds_dwordx4 v34, s[98:99]
	s_add_i32 m0, s35, 0x2000
	s_add_u32 s50, s50, 0x80080
	s_addc_u32 s51, s51, 0
	s_add_i32 s35, s72, s20
	global_load_lds_dwordx4 v142, s[98:99]
	s_mov_b32 m0, s35
	s_nop 0
	global_load_lds_dwordx4 v34, s[50:51]
	s_add_i32 m0, s35, 0x2000
	s_nop 0
	global_load_lds_dwordx4 v142, s[50:51]
	s_mov_b32 m0, s60
	s_nop 0
	global_load_lds_dwordx4 v14, s[100:101]
	s_mov_b32 m0, s61
	s_nop 0
	global_load_lds_dwordx4 v140, s[100:101]
	s_waitcnt vmcnt(8)
	s_waitcnt lgkmcnt(0)
	s_barrier
	s_setprio 1
	s_waitcnt lgkmcnt(0)
	v_mfma_f32_16x16x32_bf16 v[68:71], v[136:139], v[188:191], v[68:71]
	v_mfma_f32_16x16x32_bf16 v[64:67], v[156:159], v[188:191], v[64:67]
	v_mfma_f32_16x16x32_bf16 v[52:55], v[136:139], v[196:199], v[52:55]
	s_add_u32 s48, s48, 0x100
	v_mfma_f32_16x16x32_bf16 v[48:51], v[156:159], v[196:199], v[48:51]
	s_addc_u32 s49, s49, 0
	v_mfma_f32_16x16x32_bf16 v[36:39], v[136:139], v[214:217], v[36:39]
	s_add_u32 s13, s13, 0x100
	v_mfma_f32_16x16x32_bf16 v[30:33], v[156:159], v[214:217], v[30:33]
	s_addc_u32 s29, s29, 0
	v_mfma_f32_16x16x32_bf16 v[18:21], v[136:139], v[222:225], v[18:21]
	v_mfma_f32_16x16x32_bf16 v[10:13], v[156:159], v[222:225], v[10:13]
	v_mfma_f32_16x16x32_bf16 v[68:71], v[148:151], v[192:195], v[68:71]
	v_mfma_f32_16x16x32_bf16 v[64:67], v[160:163], v[192:195], v[64:67]
	v_mfma_f32_16x16x32_bf16 v[52:55], v[148:151], v[200:203], v[52:55]
	v_mfma_f32_16x16x32_bf16 v[48:51], v[160:163], v[200:203], v[48:51]
	v_mfma_f32_16x16x32_bf16 v[36:39], v[148:151], v[218:221], v[36:39]
	v_mfma_f32_16x16x32_bf16 v[30:33], v[160:163], v[218:221], v[30:33]
	v_mfma_f32_16x16x32_bf16 v[18:21], v[148:151], v[226:229], v[18:21]
	v_mfma_f32_16x16x32_bf16 v[10:13], v[160:163], v[226:229], v[10:13]
	s_setprio 0
	s_setprio 1
	v_mfma_f32_16x16x32_bf16 v[60:63], v[164:167], v[188:191], v[60:63]
	v_mfma_f32_16x16x32_bf16 v[56:59], v[172:175], v[188:191], v[56:59]
	v_mfma_f32_16x16x32_bf16 v[44:47], v[164:167], v[196:199], v[44:47]
	v_mfma_f32_16x16x32_bf16 v[40:43], v[172:175], v[196:199], v[40:43]
	v_mfma_f32_16x16x32_bf16 v[26:29], v[164:167], v[214:217], v[26:29]
	v_mfma_f32_16x16x32_bf16 v[22:25], v[172:175], v[214:217], v[22:25]
	v_mfma_f32_16x16x32_bf16 v[6:9], v[164:167], v[222:225], v[6:9]
	v_mfma_f32_16x16x32_bf16 v[2:5], v[172:175], v[222:225], v[2:5]
	v_mfma_f32_16x16x32_bf16 v[60:63], v[168:171], v[192:195], v[60:63]
	v_mfma_f32_16x16x32_bf16 v[56:59], v[184:187], v[192:195], v[56:59]
	v_mfma_f32_16x16x32_bf16 v[44:47], v[168:171], v[200:203], v[44:47]
	v_mfma_f32_16x16x32_bf16 v[40:43], v[184:187], v[200:203], v[40:43]
	v_mfma_f32_16x16x32_bf16 v[26:29], v[168:171], v[218:221], v[26:29]
	v_mfma_f32_16x16x32_bf16 v[22:25], v[184:187], v[218:221], v[22:25]
	v_mfma_f32_16x16x32_bf16 v[6:9], v[168:171], v[226:229], v[6:9]
	v_mfma_f32_16x16x32_bf16 v[2:5], v[184:187], v[226:229], v[2:5]
	s_setprio 0
	s_barrier
	s_cmp_ge_i32 s39, s71
	s_mov_b32 s35, s39
	s_cbranch_scc0 .LBB0_1508
	s_and_b64 vcc, exec, s[10:11]
	s_cbranch_vccz .LBB0_1511

.LBB0_1664:
	s_add_u32 s44, s42, 0xfff80080
	s_addc_u32 s45, s43, -1
	s_add_i32 s64, 0, 0x10000
	s_cmp_eq_u32 s61, 28
	s_cselect_b32 s47, s29, s45
	s_cselect_b32 s46, s53, s44
	v_add_u32_e32 v151, s64, v141
	s_cselect_b32 s45, s13, s60
	s_cselect_b32 s44, s54, s55
	s_add_i32 s67, 0, 0x14000
	ds_read_b128 v[162:165], v151
	ds_read_b128 v[166:169], v151 offset:1024
	ds_read_b128 v[170:173], v151 offset:2048
	ds_read_b128 v[174:177], v151 offset:3072
	v_add_u32_e32 v151, s67, v141
	ds_read_b128 v[184:187], v151
	ds_read_b128 v[188:191], v151 offset:1024
	ds_read_b128 v[192:195], v151 offset:2048
	ds_read_b128 v[196:199], v151 offset:3072
	s_add_i32 m0, s25, 0xc000
	ds_read_b128 v[200:203], v149
	ds_read_b128 v[214:217], v149 offset:1024
	ds_read_b128 v[218:221], v149 offset:2048
	ds_read_b128 v[222:225], v149 offset:3072
	ds_read_b128 v[226:229], v149 offset:4096
	ds_read_b128 v[230:233], v149 offset:5120
	ds_read_b128 v[234:237], v149 offset:6144
	ds_read_b128 v[238:241], v149 offset:7168
	global_load_lds_dwordx4 v142, s[42:43]
	s_add_i32 m0, s25, 0xe000
	s_nop 0
	global_load_lds_dwordx4 v144, s[42:43]
	s_waitcnt vmcnt(8)
	s_waitcnt lgkmcnt(0)
	s_barrier
	s_setprio 1
	s_waitcnt lgkmcnt(0)
	v_mfma_f32_16x16x32_bf16 v[132:135], v[162:165], v[200:203], v[132:135]
	v_mfma_f32_16x16x32_bf16 v[128:131], v[170:173], v[200:203], v[128:131]
	v_mfma_f32_16x16x32_bf16 v[116:119], v[162:165], v[218:221], v[116:119]
	s_add_u32 s98, s44, s22
	v_mfma_f32_16x16x32_bf16 v[112:115], v[170:173], v[218:221], v[112:115]
	s_addc_u32 s99, s45, s23
	v_mfma_f32_16x16x32_bf16 v[100:103], v[162:165], v[226:229], v[100:103]
	s_add_u32 s100, s46, s22
	v_mfma_f32_16x16x32_bf16 v[96:99], v[170:173], v[226:229], v[96:99]
	s_addc_u32 s101, s47, s23
	v_mfma_f32_16x16x32_bf16 v[84:87], v[162:165], v[234:237], v[84:87]
	s_add_i32 s64, s64, s20
	v_mfma_f32_16x16x32_bf16 v[80:83], v[170:173], v[234:237], v[80:83]
	s_mov_b32 m0, s64
	v_mfma_f32_16x16x32_bf16 v[132:135], v[166:169], v[214:217], v[132:135]
	v_mfma_f32_16x16x32_bf16 v[128:131], v[174:177], v[214:217], v[128:131]
	v_mfma_f32_16x16x32_bf16 v[116:119], v[166:169], v[222:225], v[116:119]
	v_mfma_f32_16x16x32_bf16 v[112:115], v[174:177], v[222:225], v[112:115]
	v_mfma_f32_16x16x32_bf16 v[100:103], v[166:169], v[230:233], v[100:103]
	v_mfma_f32_16x16x32_bf16 v[96:99], v[174:177], v[230:233], v[96:99]
	v_mfma_f32_16x16x32_bf16 v[84:87], v[166:169], v[238:241], v[84:87]
	v_mfma_f32_16x16x32_bf16 v[80:83], v[174:177], v[238:241], v[80:83]
	s_setprio 0
	s_setprio 1
	v_mfma_f32_16x16x32_bf16 v[124:127], v[184:187], v[200:203], v[124:127]
	v_mfma_f32_16x16x32_bf16 v[120:123], v[192:195], v[200:203], v[120:123]
	v_mfma_f32_16x16x32_bf16 v[108:111], v[184:187], v[218:221], v[108:111]
	v_mfma_f32_16x16x32_bf16 v[104:107], v[192:195], v[218:221], v[104:107]
	v_mfma_f32_16x16x32_bf16 v[92:95], v[184:187], v[226:229], v[92:95]
	v_mfma_f32_16x16x32_bf16 v[88:91], v[192:195], v[226:229], v[88:91]
	v_mfma_f32_16x16x32_bf16 v[76:79], v[184:187], v[234:237], v[76:79]
	v_mfma_f32_16x16x32_bf16 v[72:75], v[192:195], v[234:237], v[72:75]
	v_mfma_f32_16x16x32_bf16 v[124:127], v[188:191], v[214:217], v[124:127]
	v_mfma_f32_16x16x32_bf16 v[120:123], v[196:199], v[214:217], v[120:123]
	v_mfma_f32_16x16x32_bf16 v[108:111], v[188:191], v[222:225], v[108:111]
	v_mfma_f32_16x16x32_bf16 v[104:107], v[196:199], v[222:225], v[104:107]
	v_mfma_f32_16x16x32_bf16 v[92:95], v[188:191], v[230:233], v[92:95]
	v_mfma_f32_16x16x32_bf16 v[88:91], v[196:199], v[230:233], v[88:91]
	v_mfma_f32_16x16x32_bf16 v[76:79], v[188:191], v[238:241], v[76:79]
	v_mfma_f32_16x16x32_bf16 v[72:75], v[196:199], v[238:241], v[72:75]
	s_setprio 0
	s_barrier
	ds_read_b128 v[200:203], v149 offset:16384
	ds_read_b128 v[214:217], v149 offset:17408
	ds_read_b128 v[218:221], v149 offset:18432
	ds_read_b128 v[222:225], v149 offset:19456
	ds_read_b128 v[226:229], v149 offset:20480
	ds_read_b128 v[230:233], v149 offset:21504
	ds_read_b128 v[234:237], v149 offset:22528
	ds_read_b128 v[238:241], v149 offset:23552
	global_load_lds_dwordx4 v34, s[44:45]
	s_add_i32 m0, s64, 0x2000
	s_add_u32 s64, s44, 0x80000
	s_addc_u32 s65, s45, 0
	s_add_i32 s67, s67, s20
	global_load_lds_dwordx4 v14, s[44:45]
	s_mov_b32 m0, s67
	s_nop 0
	global_load_lds_dwordx4 v34, s[64:65]
	s_add_i32 m0, s67, 0x2000
	s_nop 0
	global_load_lds_dwordx4 v14, s[64:65]
	s_mov_b32 m0, s25
	s_nop 0
	global_load_lds_dwordx4 v138, s[46:47]
	s_mov_b32 m0, s26
	s_nop 0
	global_load_lds_dwordx4 v136, s[46:47]
	s_waitcnt vmcnt(8)
	s_waitcnt lgkmcnt(0)
	s_barrier
	s_setprio 1
	s_waitcnt lgkmcnt(0)
	v_mfma_f32_16x16x32_bf16 v[68:71], v[162:165], v[200:203], v[68:71]
	v_mfma_f32_16x16x32_bf16 v[64:67], v[170:173], v[200:203], v[64:67]
	v_mfma_f32_16x16x32_bf16 v[52:55], v[162:165], v[218:221], v[52:55]
	s_add_i32 s64, 0, 0x18000
	v_mfma_f32_16x16x32_bf16 v[48:51], v[170:173], v[218:221], v[48:51]
	v_mfma_f32_16x16x32_bf16 v[36:39], v[162:165], v[226:229], v[36:39]
	v_mfma_f32_16x16x32_bf16 v[30:33], v[170:173], v[226:229], v[30:33]
	v_mfma_f32_16x16x32_bf16 v[18:21], v[162:165], v[234:237], v[18:21]
	v_mfma_f32_16x16x32_bf16 v[10:13], v[170:173], v[234:237], v[10:13]
	v_mfma_f32_16x16x32_bf16 v[68:71], v[166:169], v[214:217], v[68:71]
	v_mfma_f32_16x16x32_bf16 v[64:67], v[174:177], v[214:217], v[64:67]
	v_mfma_f32_16x16x32_bf16 v[52:55], v[166:169], v[222:225], v[52:55]
	v_mfma_f32_16x16x32_bf16 v[48:51], v[174:177], v[222:225], v[48:51]
	v_mfma_f32_16x16x32_bf16 v[36:39], v[166:169], v[230:233], v[36:39]
	v_mfma_f32_16x16x32_bf16 v[30:33], v[174:177], v[230:233], v[30:33]
	v_mfma_f32_16x16x32_bf16 v[18:21], v[166:169], v[238:241], v[18:21]
	v_mfma_f32_16x16x32_bf16 v[10:13], v[174:177], v[238:241], v[10:13]
	s_setprio 0
	s_setprio 1
	v_mfma_f32_16x16x32_bf16 v[60:63], v[184:187], v[200:203], v[60:63]
	v_mfma_f32_16x16x32_bf16 v[56:59], v[192:195], v[200:203], v[56:59]
	v_mfma_f32_16x16x32_bf16 v[44:47], v[184:187], v[218:221], v[44:47]
	v_mfma_f32_16x16x32_bf16 v[40:43], v[192:195], v[218:221], v[40:43]
	v_mfma_f32_16x16x32_bf16 v[26:29], v[184:187], v[226:229], v[26:29]
	v_mfma_f32_16x16x32_bf16 v[22:25], v[192:195], v[226:229], v[22:25]
	v_mfma_f32_16x16x32_bf16 v[6:9], v[184:187], v[234:237], v[6:9]
	v_mfma_f32_16x16x32_bf16 v[2:5], v[192:195], v[234:237], v[2:5]
	v_mfma_f32_16x16x32_bf16 v[60:63], v[188:191], v[214:217], v[60:63]
	v_mfma_f32_16x16x32_bf16 v[56:59], v[196:199], v[214:217], v[56:59]
	v_mfma_f32_16x16x32_bf16 v[44:47], v[188:191], v[222:225], v[44:47]
	v_mfma_f32_16x16x32_bf16 v[40:43], v[196:199], v[222:225], v[40:43]
	v_mfma_f32_16x16x32_bf16 v[26:29], v[188:191], v[230:233], v[26:29]
	v_mfma_f32_16x16x32_bf16 v[22:25], v[196:199], v[230:233], v[22:25]
	v_mfma_f32_16x16x32_bf16 v[6:9], v[188:191], v[238:241], v[6:9]
	v_mfma_f32_16x16x32_bf16 v[2:5], v[196:199], v[238:241], v[2:5]
	s_setprio 0
	s_barrier
	v_add_u32_e32 v151, s64, v141
	s_add_i32 s65, 0, 0x1c000
	ds_read_b128 v[162:165], v151
	ds_read_b128 v[166:169], v151 offset:1024
	ds_read_b128 v[170:173], v151 offset:2048
	ds_read_b128 v[174:177], v151 offset:3072
	v_add_u32_e32 v151, s65, v141
	ds_read_b128 v[184:187], v151
	ds_read_b128 v[188:191], v151 offset:1024
	ds_read_b128 v[192:195], v151 offset:2048
	ds_read_b128 v[196:199], v151 offset:3072
	s_add_u32 s46, s46, 0x80000
	s_addc_u32 s47, s47, 0
	s_mov_b32 m0, s27
	ds_read_b128 v[200:203], v149 offset:32768
	ds_read_b128 v[214:217], v149 offset:33792
	ds_read_b128 v[218:221], v149 offset:34816
	ds_read_b128 v[222:225], v149 offset:35840
	ds_read_b128 v[226:229], v149 offset:36864
	ds_read_b128 v[230:233], v149 offset:37888
	ds_read_b128 v[234:237], v149 offset:38912
	ds_read_b128 v[238:241], v149 offset:39936
	global_load_lds_dwordx4 v138, s[46:47]
	s_mov_b32 m0, s31
	s_nop 0
	global_load_lds_dwordx4 v136, s[46:47]
	s_waitcnt vmcnt(8)
	s_waitcnt lgkmcnt(0)
	s_barrier
	s_setprio 1
	s_waitcnt lgkmcnt(0)
	v_mfma_f32_16x16x32_bf16 v[132:135], v[162:165], v[200:203], v[132:135]
	v_mfma_f32_16x16x32_bf16 v[128:131], v[170:173], v[200:203], v[128:131]
	v_mfma_f32_16x16x32_bf16 v[116:119], v[162:165], v[218:221], v[116:119]
	s_add_i32 s46, s64, s20
	v_mfma_f32_16x16x32_bf16 v[112:115], v[170:173], v[218:221], v[112:115]
	s_mov_b32 m0, s46
	v_mfma_f32_16x16x32_bf16 v[100:103], v[162:165], v[226:229], v[100:103]
	v_mfma_f32_16x16x32_bf16 v[96:99], v[170:173], v[226:229], v[96:99]
	v_mfma_f32_16x16x32_bf16 v[84:87], v[162:165], v[234:237], v[84:87]
	v_mfma_f32_16x16x32_bf16 v[80:83], v[170:173], v[234:237], v[80:83]
	v_mfma_f32_16x16x32_bf16 v[132:135], v[166:169], v[214:217], v[132:135]
	v_mfma_f32_16x16x32_bf16 v[128:131], v[174:177], v[214:217], v[128:131]
	v_mfma_f32_16x16x32_bf16 v[116:119], v[166:169], v[222:225], v[116:119]
	v_mfma_f32_16x16x32_bf16 v[112:115], v[174:177], v[222:225], v[112:115]
	v_mfma_f32_16x16x32_bf16 v[100:103], v[166:169], v[230:233], v[100:103]
	v_mfma_f32_16x16x32_bf16 v[96:99], v[174:177], v[230:233], v[96:99]
	v_mfma_f32_16x16x32_bf16 v[84:87], v[166:169], v[238:241], v[84:87]
	v_mfma_f32_16x16x32_bf16 v[80:83], v[174:177], v[238:241], v[80:83]
	s_setprio 0
	s_setprio 1
	v_mfma_f32_16x16x32_bf16 v[124:127], v[184:187], v[200:203], v[124:127]
	v_mfma_f32_16x16x32_bf16 v[120:123], v[192:195], v[200:203], v[120:123]
	v_mfma_f32_16x16x32_bf16 v[108:111], v[184:187], v[218:221], v[108:111]
	v_mfma_f32_16x16x32_bf16 v[104:107], v[192:195], v[218:221], v[104:107]
	v_mfma_f32_16x16x32_bf16 v[92:95], v[184:187], v[226:229], v[92:95]
	v_mfma_f32_16x16x32_bf16 v[88:91], v[192:195], v[226:229], v[88:91]
	v_mfma_f32_16x16x32_bf16 v[76:79], v[184:187], v[234:237], v[76:79]
	v_mfma_f32_16x16x32_bf16 v[72:75], v[192:195], v[234:237], v[72:75]
	v_mfma_f32_16x16x32_bf16 v[124:127], v[188:191], v[214:217], v[124:127]
	v_mfma_f32_16x16x32_bf16 v[120:123], v[196:199], v[214:217], v[120:123]
	v_mfma_f32_16x16x32_bf16 v[108:111], v[188:191], v[222:225], v[108:111]
	v_mfma_f32_16x16x32_bf16 v[104:107], v[196:199], v[222:225], v[104:107]
	v_mfma_f32_16x16x32_bf16 v[92:95], v[188:191], v[230:233], v[92:95]
	v_mfma_f32_16x16x32_bf16 v[88:91], v[196:199], v[230:233], v[88:91]
	v_mfma_f32_16x16x32_bf16 v[76:79], v[188:191], v[238:241], v[76:79]
	v_mfma_f32_16x16x32_bf16 v[72:75], v[196:199], v[238:241], v[72:75]
	s_setprio 0
	s_barrier
	ds_read_b128 v[200:203], v149 offset:49152
	ds_read_b128 v[214:217], v149 offset:50176
	ds_read_b128 v[218:221], v149 offset:51200
	ds_read_b128 v[222:225], v149 offset:52224
	ds_read_b128 v[226:229], v149 offset:53248
	ds_read_b128 v[230:233], v149 offset:54272
	ds_read_b128 v[234:237], v149 offset:55296
	ds_read_b128 v[238:241], v149 offset:56320
	global_load_lds_dwordx4 v34, s[98:99]
	s_add_i32 m0, s46, 0x2000
	s_add_u32 s44, s44, 0x80080
	s_addc_u32 s45, s45, 0
	s_add_i32 s46, s65, s20
	global_load_lds_dwordx4 v14, s[98:99]
	s_mov_b32 m0, s46
	s_nop 0
	global_load_lds_dwordx4 v34, s[44:45]
	s_add_i32 m0, s46, 0x2000
	s_nop 0
	global_load_lds_dwordx4 v14, s[44:45]
	s_mov_b32 m0, s48
	s_nop 0
	global_load_lds_dwordx4 v138, s[100:101]
	s_mov_b32 m0, s49
	s_nop 0
	global_load_lds_dwordx4 v136, s[100:101]
	s_waitcnt vmcnt(8)
	s_waitcnt lgkmcnt(0)
	s_barrier
	s_setprio 1
	s_waitcnt lgkmcnt(0)
	v_mfma_f32_16x16x32_bf16 v[68:71], v[162:165], v[200:203], v[68:71]
	v_mfma_f32_16x16x32_bf16 v[64:67], v[170:173], v[200:203], v[64:67]
	v_mfma_f32_16x16x32_bf16 v[52:55], v[162:165], v[218:221], v[52:55]
	s_add_i32 s61, s61, 2
	v_mfma_f32_16x16x32_bf16 v[48:51], v[170:173], v[218:221], v[48:51]
	s_add_u32 s42, s42, 0x100
	v_mfma_f32_16x16x32_bf16 v[36:39], v[162:165], v[226:229], v[36:39]
	s_addc_u32 s43, s43, 0
	v_mfma_f32_16x16x32_bf16 v[30:33], v[170:173], v[226:229], v[30:33]
	s_add_u32 s55, s55, 0x100
	v_mfma_f32_16x16x32_bf16 v[18:21], v[162:165], v[234:237], v[18:21]
	s_addc_u32 s60, s60, 0
	v_mfma_f32_16x16x32_bf16 v[10:13], v[170:173], v[234:237], v[10:13]
	v_mfma_f32_16x16x32_bf16 v[68:71], v[166:169], v[214:217], v[68:71]
	v_mfma_f32_16x16x32_bf16 v[64:67], v[174:177], v[214:217], v[64:67]
	v_mfma_f32_16x16x32_bf16 v[52:55], v[166:169], v[222:225], v[52:55]
	v_mfma_f32_16x16x32_bf16 v[48:51], v[174:177], v[222:225], v[48:51]
	v_mfma_f32_16x16x32_bf16 v[36:39], v[166:169], v[230:233], v[36:39]
	v_mfma_f32_16x16x32_bf16 v[30:33], v[174:177], v[230:233], v[30:33]
	v_mfma_f32_16x16x32_bf16 v[18:21], v[166:169], v[238:241], v[18:21]
	v_mfma_f32_16x16x32_bf16 v[10:13], v[174:177], v[238:241], v[10:13]
	s_setprio 0
	s_setprio 1
	v_mfma_f32_16x16x32_bf16 v[60:63], v[184:187], v[200:203], v[60:63]
	v_mfma_f32_16x16x32_bf16 v[56:59], v[192:195], v[200:203], v[56:59]
	v_mfma_f32_16x16x32_bf16 v[44:47], v[184:187], v[218:221], v[44:47]
	v_mfma_f32_16x16x32_bf16 v[40:43], v[192:195], v[218:221], v[40:43]
	v_mfma_f32_16x16x32_bf16 v[26:29], v[184:187], v[226:229], v[26:29]
	v_mfma_f32_16x16x32_bf16 v[22:25], v[192:195], v[226:229], v[22:25]
	v_mfma_f32_16x16x32_bf16 v[6:9], v[184:187], v[234:237], v[6:9]
	v_mfma_f32_16x16x32_bf16 v[2:5], v[192:195], v[234:237], v[2:5]
	v_mfma_f32_16x16x32_bf16 v[60:63], v[188:191], v[214:217], v[60:63]
	v_mfma_f32_16x16x32_bf16 v[56:59], v[196:199], v[214:217], v[56:59]
	v_mfma_f32_16x16x32_bf16 v[44:47], v[188:191], v[222:225], v[44:47]
	v_mfma_f32_16x16x32_bf16 v[40:43], v[196:199], v[222:225], v[40:43]
	v_mfma_f32_16x16x32_bf16 v[26:29], v[188:191], v[230:233], v[26:29]
	v_mfma_f32_16x16x32_bf16 v[22:25], v[196:199], v[230:233], v[22:25]
	v_mfma_f32_16x16x32_bf16 v[6:9], v[188:191], v[238:241], v[6:9]
	v_mfma_f32_16x16x32_bf16 v[2:5], v[196:199], v[238:241], v[2:5]
	s_setprio 0
	s_barrier
	s_cmp_gt_u32 s61, 29
	s_cbranch_scc0 .LBB0_1664
	s_and_b64 vcc, exec, s[10:11]
	s_cbranch_vccz .LBB0_1667
	s_barrier

.LBB0_1764:
	s_add_i32 vcc_lo, s44, 2
	s_add_u32 s42, s36, 0x100
	s_addc_u32 s43, s37, 0
	s_add_i32 s72, 0, 0x10000
	s_cmp_eq_u32 s11, s44
	s_cselect_b32 s47, s13, s43
	s_cselect_b32 s46, s12, s42
	s_cselect_b32 s45, s29, s71
	s_cselect_b32 s44, s28, s70
	s_add_i32 s73, 0, 0x14000
	v_add_u32_e32 v160, s72, v152
	v_add_u32_e32 v176, s73, v152
	ds_read_b128 v[136:139], v160
	ds_read_b128 v[148:151], v160 offset:1024
	ds_read_b128 v[156:159], v160 offset:2048
	ds_read_b128 v[160:163], v160 offset:3072
	ds_read_b128 v[164:167], v176
	ds_read_b128 v[168:171], v176 offset:1024
	ds_read_b128 v[172:175], v176 offset:2048
	ds_read_b128 v[184:187], v176 offset:3072
	s_add_i32 m0, s25, 0xc000
	ds_read_b128 v[188:191], v155
	ds_read_b128 v[192:195], v155 offset:1024
	ds_read_b128 v[196:199], v155 offset:2048
	ds_read_b128 v[200:203], v155 offset:3072
	ds_read_b128 v[214:217], v155 offset:4096
	ds_read_b128 v[218:221], v155 offset:5120
	ds_read_b128 v[222:225], v155 offset:6144
	ds_read_b128 v[226:229], v155 offset:7168
	global_load_lds_dwordx4 v144, s[36:37]
	s_add_i32 m0, s25, 0xe000
	s_nop 0
	global_load_lds_dwordx4 v146, s[36:37]
	s_waitcnt vmcnt(8)
	s_waitcnt lgkmcnt(0)
	s_barrier
	s_setprio 1
	s_waitcnt lgkmcnt(0)
	v_mfma_f32_16x16x32_bf16 v[132:135], v[136:139], v[188:191], v[132:135]
	v_mfma_f32_16x16x32_bf16 v[128:131], v[156:159], v[188:191], v[128:131]
	v_mfma_f32_16x16x32_bf16 v[116:119], v[136:139], v[196:199], v[116:119]
	s_add_u32 s98, s44, s22
	v_mfma_f32_16x16x32_bf16 v[112:115], v[156:159], v[196:199], v[112:115]
	s_addc_u32 s99, s45, s23
	v_mfma_f32_16x16x32_bf16 v[100:103], v[136:139], v[214:217], v[100:103]
	s_add_u32 s100, s46, s22
	v_mfma_f32_16x16x32_bf16 v[96:99], v[156:159], v[214:217], v[96:99]
	s_addc_u32 s101, s47, s23
	v_mfma_f32_16x16x32_bf16 v[84:87], v[136:139], v[222:225], v[84:87]
	s_add_i32 s36, s72, s20
	v_mfma_f32_16x16x32_bf16 v[80:83], v[156:159], v[222:225], v[80:83]
	s_mov_b32 m0, s36
	v_mfma_f32_16x16x32_bf16 v[132:135], v[148:151], v[192:195], v[132:135]
	v_mfma_f32_16x16x32_bf16 v[128:131], v[160:163], v[192:195], v[128:131]
	v_mfma_f32_16x16x32_bf16 v[116:119], v[148:151], v[200:203], v[116:119]
	v_mfma_f32_16x16x32_bf16 v[112:115], v[160:163], v[200:203], v[112:115]
	v_mfma_f32_16x16x32_bf16 v[100:103], v[148:151], v[218:221], v[100:103]
	v_mfma_f32_16x16x32_bf16 v[96:99], v[160:163], v[218:221], v[96:99]
	v_mfma_f32_16x16x32_bf16 v[84:87], v[148:151], v[226:229], v[84:87]
	v_mfma_f32_16x16x32_bf16 v[80:83], v[160:163], v[226:229], v[80:83]
	s_setprio 0
	s_setprio 1
	v_mfma_f32_16x16x32_bf16 v[124:127], v[164:167], v[188:191], v[124:127]
	v_mfma_f32_16x16x32_bf16 v[120:123], v[172:175], v[188:191], v[120:123]
	v_mfma_f32_16x16x32_bf16 v[108:111], v[164:167], v[196:199], v[108:111]
	v_mfma_f32_16x16x32_bf16 v[104:107], v[172:175], v[196:199], v[104:107]
	v_mfma_f32_16x16x32_bf16 v[92:95], v[164:167], v[214:217], v[92:95]
	v_mfma_f32_16x16x32_bf16 v[88:91], v[172:175], v[214:217], v[88:91]
	v_mfma_f32_16x16x32_bf16 v[76:79], v[164:167], v[222:225], v[76:79]
	v_mfma_f32_16x16x32_bf16 v[72:75], v[172:175], v[222:225], v[72:75]
	v_mfma_f32_16x16x32_bf16 v[124:127], v[168:171], v[192:195], v[124:127]
	v_mfma_f32_16x16x32_bf16 v[120:123], v[184:187], v[192:195], v[120:123]
	v_mfma_f32_16x16x32_bf16 v[108:111], v[168:171], v[200:203], v[108:111]
	v_mfma_f32_16x16x32_bf16 v[104:107], v[184:187], v[200:203], v[104:107]
	v_mfma_f32_16x16x32_bf16 v[92:95], v[168:171], v[218:221], v[92:95]
	v_mfma_f32_16x16x32_bf16 v[88:91], v[184:187], v[218:221], v[88:91]
	v_mfma_f32_16x16x32_bf16 v[76:79], v[168:171], v[226:229], v[76:79]
	v_mfma_f32_16x16x32_bf16 v[72:75], v[184:187], v[226:229], v[72:75]
	s_setprio 0
	s_barrier
	ds_read_b128 v[188:191], v155 offset:16384
	ds_read_b128 v[192:195], v155 offset:17408
	ds_read_b128 v[196:199], v155 offset:18432
	ds_read_b128 v[200:203], v155 offset:19456
	ds_read_b128 v[214:217], v155 offset:20480
	ds_read_b128 v[218:221], v155 offset:21504
	ds_read_b128 v[222:225], v155 offset:22528
	ds_read_b128 v[226:229], v155 offset:23552
	global_load_lds_dwordx4 v34, s[44:45]
	s_add_i32 m0, s36, 0x2000
	s_add_u32 s36, s44, 0x160000
	s_addc_u32 s37, s45, 0
	s_add_i32 s72, s73, s20
	global_load_lds_dwordx4 v142, s[44:45]
	s_mov_b32 m0, s72
	s_nop 0
	global_load_lds_dwordx4 v34, s[36:37]
	s_add_i32 m0, s72, 0x2000
	s_nop 0
	global_load_lds_dwordx4 v142, s[36:37]
	s_mov_b32 m0, s25
	s_nop 0
	global_load_lds_dwordx4 v14, s[46:47]
	s_mov_b32 m0, s26
	s_nop 0
	global_load_lds_dwordx4 v140, s[46:47]
	s_waitcnt vmcnt(8)
	s_waitcnt lgkmcnt(0)
	s_barrier
	s_setprio 1
	s_waitcnt lgkmcnt(0)
	v_mfma_f32_16x16x32_bf16 v[68:71], v[136:139], v[188:191], v[68:71]
	v_mfma_f32_16x16x32_bf16 v[64:67], v[156:159], v[188:191], v[64:67]
	v_mfma_f32_16x16x32_bf16 v[52:55], v[136:139], v[196:199], v[52:55]
	s_add_i32 s72, 0, 0x18000
	v_mfma_f32_16x16x32_bf16 v[48:51], v[156:159], v[196:199], v[48:51]
	s_add_i32 s73, 0, 0x1c000
	v_mfma_f32_16x16x32_bf16 v[36:39], v[136:139], v[214:217], v[36:39]
	v_mfma_f32_16x16x32_bf16 v[30:33], v[156:159], v[214:217], v[30:33]
	v_mfma_f32_16x16x32_bf16 v[18:21], v[136:139], v[222:225], v[18:21]
	v_mfma_f32_16x16x32_bf16 v[10:13], v[156:159], v[222:225], v[10:13]
	v_mfma_f32_16x16x32_bf16 v[68:71], v[148:151], v[192:195], v[68:71]
	v_mfma_f32_16x16x32_bf16 v[64:67], v[160:163], v[192:195], v[64:67]
	v_mfma_f32_16x16x32_bf16 v[52:55], v[148:151], v[200:203], v[52:55]
	v_mfma_f32_16x16x32_bf16 v[48:51], v[160:163], v[200:203], v[48:51]
	v_mfma_f32_16x16x32_bf16 v[36:39], v[148:151], v[218:221], v[36:39]
	v_mfma_f32_16x16x32_bf16 v[30:33], v[160:163], v[218:221], v[30:33]
	v_mfma_f32_16x16x32_bf16 v[18:21], v[148:151], v[226:229], v[18:21]
	v_mfma_f32_16x16x32_bf16 v[10:13], v[160:163], v[226:229], v[10:13]
	s_setprio 0
	s_setprio 1
	v_mfma_f32_16x16x32_bf16 v[60:63], v[164:167], v[188:191], v[60:63]
	v_mfma_f32_16x16x32_bf16 v[56:59], v[172:175], v[188:191], v[56:59]
	v_mfma_f32_16x16x32_bf16 v[44:47], v[164:167], v[196:199], v[44:47]
	v_mfma_f32_16x16x32_bf16 v[40:43], v[172:175], v[196:199], v[40:43]
	v_mfma_f32_16x16x32_bf16 v[26:29], v[164:167], v[214:217], v[26:29]
	v_mfma_f32_16x16x32_bf16 v[22:25], v[172:175], v[214:217], v[22:25]
	v_mfma_f32_16x16x32_bf16 v[6:9], v[164:167], v[222:225], v[6:9]
	v_mfma_f32_16x16x32_bf16 v[2:5], v[172:175], v[222:225], v[2:5]
	v_mfma_f32_16x16x32_bf16 v[60:63], v[168:171], v[192:195], v[60:63]
	v_mfma_f32_16x16x32_bf16 v[56:59], v[184:187], v[192:195], v[56:59]
	v_mfma_f32_16x16x32_bf16 v[44:47], v[168:171], v[200:203], v[44:47]
	v_mfma_f32_16x16x32_bf16 v[40:43], v[184:187], v[200:203], v[40:43]
	v_mfma_f32_16x16x32_bf16 v[26:29], v[168:171], v[218:221], v[26:29]
	v_mfma_f32_16x16x32_bf16 v[22:25], v[184:187], v[218:221], v[22:25]
	v_mfma_f32_16x16x32_bf16 v[6:9], v[168:171], v[226:229], v[6:9]
	v_mfma_f32_16x16x32_bf16 v[2:5], v[184:187], v[226:229], v[2:5]
	s_setprio 0
	s_barrier
	v_add_u32_e32 v160, s72, v152
	v_add_u32_e32 v183, s73, v152
	ds_read_b128 v[136:139], v160
	ds_read_b128 v[148:151], v160 offset:1024
	ds_read_b128 v[156:159], v160 offset:2048
	ds_read_b128 v[160:163], v160 offset:3072
	ds_read_b128 v[164:167], v183
	ds_read_b128 v[168:171], v183 offset:1024
	ds_read_b128 v[172:175], v183 offset:2048
	ds_read_b128 v[184:187], v183 offset:3072
	s_add_u32 s36, s46, 0x160000
	s_addc_u32 s37, s47, 0
	s_mov_b32 m0, s27
	ds_read_b128 v[188:191], v155 offset:32768
	ds_read_b128 v[192:195], v155 offset:33792
	ds_read_b128 v[196:199], v155 offset:34816
	ds_read_b128 v[200:203], v155 offset:35840
	ds_read_b128 v[214:217], v155 offset:36864
	ds_read_b128 v[218:221], v155 offset:37888
	ds_read_b128 v[222:225], v155 offset:38912
	ds_read_b128 v[226:229], v155 offset:39936
	global_load_lds_dwordx4 v14, s[36:37]
	s_mov_b32 m0, s31
	s_nop 0
	global_load_lds_dwordx4 v140, s[36:37]
	s_waitcnt vmcnt(8)
	s_waitcnt lgkmcnt(0)
	s_barrier
	s_setprio 1
	s_waitcnt lgkmcnt(0)
	v_mfma_f32_16x16x32_bf16 v[132:135], v[136:139], v[188:191], v[132:135]
	v_mfma_f32_16x16x32_bf16 v[128:131], v[156:159], v[188:191], v[128:131]
	v_mfma_f32_16x16x32_bf16 v[116:119], v[136:139], v[196:199], v[116:119]
	s_add_i32 s36, s72, s20
	v_mfma_f32_16x16x32_bf16 v[112:115], v[156:159], v[196:199], v[112:115]
	s_mov_b32 m0, s36
	v_mfma_f32_16x16x32_bf16 v[100:103], v[136:139], v[214:217], v[100:103]
	v_mfma_f32_16x16x32_bf16 v[96:99], v[156:159], v[214:217], v[96:99]
	v_mfma_f32_16x16x32_bf16 v[84:87], v[136:139], v[222:225], v[84:87]
	v_mfma_f32_16x16x32_bf16 v[80:83], v[156:159], v[222:225], v[80:83]
	v_mfma_f32_16x16x32_bf16 v[132:135], v[148:151], v[192:195], v[132:135]
	v_mfma_f32_16x16x32_bf16 v[128:131], v[160:163], v[192:195], v[128:131]
	v_mfma_f32_16x16x32_bf16 v[116:119], v[148:151], v[200:203], v[116:119]
	v_mfma_f32_16x16x32_bf16 v[112:115], v[160:163], v[200:203], v[112:115]
	v_mfma_f32_16x16x32_bf16 v[100:103], v[148:151], v[218:221], v[100:103]
	v_mfma_f32_16x16x32_bf16 v[96:99], v[160:163], v[218:221], v[96:99]
	v_mfma_f32_16x16x32_bf16 v[84:87], v[148:151], v[226:229], v[84:87]
	v_mfma_f32_16x16x32_bf16 v[80:83], v[160:163], v[226:229], v[80:83]
	s_setprio 0
	s_setprio 1
	v_mfma_f32_16x16x32_bf16 v[124:127], v[164:167], v[188:191], v[124:127]
	v_mfma_f32_16x16x32_bf16 v[120:123], v[172:175], v[188:191], v[120:123]
	v_mfma_f32_16x16x32_bf16 v[108:111], v[164:167], v[196:199], v[108:111]
	v_mfma_f32_16x16x32_bf16 v[104:107], v[172:175], v[196:199], v[104:107]
	v_mfma_f32_16x16x32_bf16 v[92:95], v[164:167], v[214:217], v[92:95]
	v_mfma_f32_16x16x32_bf16 v[88:91], v[172:175], v[214:217], v[88:91]
	v_mfma_f32_16x16x32_bf16 v[76:79], v[164:167], v[222:225], v[76:79]
	v_mfma_f32_16x16x32_bf16 v[72:75], v[172:175], v[222:225], v[72:75]
	v_mfma_f32_16x16x32_bf16 v[124:127], v[168:171], v[192:195], v[124:127]
	v_mfma_f32_16x16x32_bf16 v[120:123], v[184:187], v[192:195], v[120:123]
	v_mfma_f32_16x16x32_bf16 v[108:111], v[168:171], v[200:203], v[108:111]
	v_mfma_f32_16x16x32_bf16 v[104:107], v[184:187], v[200:203], v[104:107]
	v_mfma_f32_16x16x32_bf16 v[92:95], v[168:171], v[218:221], v[92:95]
	v_mfma_f32_16x16x32_bf16 v[88:91], v[184:187], v[218:221], v[88:91]
	v_mfma_f32_16x16x32_bf16 v[76:79], v[168:171], v[226:229], v[76:79]
	v_mfma_f32_16x16x32_bf16 v[72:75], v[184:187], v[226:229], v[72:75]
	s_setprio 0
	s_barrier
	ds_read_b128 v[188:191], v155 offset:49152
	ds_read_b128 v[192:195], v155 offset:50176
	ds_read_b128 v[196:199], v155 offset:51200
	ds_read_b128 v[200:203], v155 offset:52224
	ds_read_b128 v[214:217], v155 offset:53248
	ds_read_b128 v[218:221], v155 offset:54272
	ds_read_b128 v[222:225], v155 offset:55296
	ds_read_b128 v[226:229], v155 offset:56320
	global_load_lds_dwordx4 v34, s[98:99]
	s_add_i32 m0, s36, 0x2000
	s_add_u32 s36, s44, 0x160080
	s_addc_u32 s37, s45, 0
	s_add_i32 s44, s73, s20
	global_load_lds_dwordx4 v142, s[98:99]
	s_mov_b32 m0, s44
	s_nop 0
	global_load_lds_dwordx4 v34, s[36:37]
	s_add_i32 m0, s44, 0x2000
	s_nop 0
	global_load_lds_dwordx4 v142, s[36:37]
	s_mov_b32 m0, s50
	s_nop 0
	global_load_lds_dwordx4 v14, s[100:101]
	s_mov_b32 m0, s51
	s_nop 0
	global_load_lds_dwordx4 v140, s[100:101]
	s_waitcnt vmcnt(8)
	s_waitcnt lgkmcnt(0)
	s_barrier
	s_setprio 1
	s_waitcnt lgkmcnt(0)
	v_mfma_f32_16x16x32_bf16 v[68:71], v[136:139], v[188:191], v[68:71]
	v_mfma_f32_16x16x32_bf16 v[64:67], v[156:159], v[188:191], v[64:67]
	v_mfma_f32_16x16x32_bf16 v[52:55], v[136:139], v[196:199], v[52:55]
	s_add_u32 s70, s70, 0x100
	v_mfma_f32_16x16x32_bf16 v[48:51], v[156:159], v[196:199], v[48:51]
	s_addc_u32 s71, s71, 0
	v_mfma_f32_16x16x32_bf16 v[36:39], v[136:139], v[214:217], v[36:39]
	v_mfma_f32_16x16x32_bf16 v[30:33], v[156:159], v[214:217], v[30:33]
	v_mfma_f32_16x16x32_bf16 v[18:21], v[136:139], v[222:225], v[18:21]
	v_mfma_f32_16x16x32_bf16 v[10:13], v[156:159], v[222:225], v[10:13]
	v_mfma_f32_16x16x32_bf16 v[68:71], v[148:151], v[192:195], v[68:71]
	v_mfma_f32_16x16x32_bf16 v[64:67], v[160:163], v[192:195], v[64:67]
	v_mfma_f32_16x16x32_bf16 v[52:55], v[148:151], v[200:203], v[52:55]
	v_mfma_f32_16x16x32_bf16 v[48:51], v[160:163], v[200:203], v[48:51]
	v_mfma_f32_16x16x32_bf16 v[36:39], v[148:151], v[218:221], v[36:39]
	v_mfma_f32_16x16x32_bf16 v[30:33], v[160:163], v[218:221], v[30:33]
	v_mfma_f32_16x16x32_bf16 v[18:21], v[148:151], v[226:229], v[18:21]
	v_mfma_f32_16x16x32_bf16 v[10:13], v[160:163], v[226:229], v[10:13]
	s_setprio 0
	s_setprio 1
	v_mfma_f32_16x16x32_bf16 v[60:63], v[164:167], v[188:191], v[60:63]
	v_mfma_f32_16x16x32_bf16 v[56:59], v[172:175], v[188:191], v[56:59]
	v_mfma_f32_16x16x32_bf16 v[44:47], v[164:167], v[196:199], v[44:47]
	v_mfma_f32_16x16x32_bf16 v[40:43], v[172:175], v[196:199], v[40:43]
	v_mfma_f32_16x16x32_bf16 v[26:29], v[164:167], v[214:217], v[26:29]
	v_mfma_f32_16x16x32_bf16 v[22:25], v[172:175], v[214:217], v[22:25]
	v_mfma_f32_16x16x32_bf16 v[6:9], v[164:167], v[222:225], v[6:9]
	v_mfma_f32_16x16x32_bf16 v[2:5], v[172:175], v[222:225], v[2:5]
	v_mfma_f32_16x16x32_bf16 v[60:63], v[168:171], v[192:195], v[60:63]
	v_mfma_f32_16x16x32_bf16 v[56:59], v[184:187], v[192:195], v[56:59]
	v_mfma_f32_16x16x32_bf16 v[44:47], v[168:171], v[200:203], v[44:47]
	v_mfma_f32_16x16x32_bf16 v[40:43], v[184:187], v[200:203], v[40:43]
	v_mfma_f32_16x16x32_bf16 v[26:29], v[168:171], v[218:221], v[26:29]
	v_mfma_f32_16x16x32_bf16 v[22:25], v[184:187], v[218:221], v[22:25]
	v_mfma_f32_16x16x32_bf16 v[6:9], v[168:171], v[226:229], v[6:9]
	v_mfma_f32_16x16x32_bf16 v[2:5], v[184:187], v[226:229], v[2:5]
	s_setprio 0
	s_barrier
	s_cmp_ge_i32 vcc_lo, s67
	s_mov_b64 s[36:37], s[42:43]
	s_mov_b32 s44, vcc_lo
	s_cbranch_scc0 .LBB0_1764
	s_mov_b32 s71, 0x200000
	s_and_b64 vcc, exec, s[8:9]
	s_cbranch_vccz .LBB0_1767
